# conv tile: 30 of 32 depthwise weight/bias loads issued early into the freed halo registers (hidden behind GLU math)
# baseline (speedup 1.0000x reference)
; __device__ __forceinline__ void conv_tile(const Params& p, int l, int item, const bf16* PROJ, bf16* CV, LAS float* sl) {
;     ...
; #pragma unroll
;     for (int rr = 0; rr < 62; ++rr) { const int sq = s0 - 15 + rr; const bool ok = sq >= 0 && sq < SEQ; const bf16* pr = PROJ + (size_t)(b * SEQ + (ok ? sq : s0)) * NIN;
;         const float a = bf2f(pr[PB_A + c]), g = bf2f(pr[PB_G + c]); u[rr] = ok ? a / (1.0f + __expf(-g)) : 0.f; }
;     float w[31];
; #pragma unroll
;     for (int j = 0; j < 31; ++j) w[j] = p.conv_dw[(size_t)(l * 31 + j) * CC + c];
;     const float bias = p.conv_dw_b[l * CC + c];
.LBB0_329:
	v_mad_u64_u32 v[8:9], s[8:9], s74, v195, v[4:5]
	v_add_co_u32_e32 v30, vcc, 0x1000, v8
	s_nop 0
	s_nop 0
	v_addc_co_u32_e32 v31, vcc, 0, v9, vcc
	global_load_ushort v97, v[30:31], off
	s_nop 0
	global_load_ushort v30, v[8:9], off offset:3072
	v_mad_u64_u32 v[8:9], s[8:9], s14, v195, v[4:5]
	v_add_co_u32_e32 v32, vcc, 0x1000, v8
	s_nop 0
	s_nop 0
	v_addc_co_u32_e32 v33, vcc, 0, v9, vcc
	global_load_ushort v34, v[32:33], off
	global_load_ushort v13, v[8:9], off offset:3072
	v_mad_u64_u32 v[8:9], s[8:9], s12, v195, v[4:5]
	v_add_co_u32_e32 v32, vcc, 0x1000, v8
	s_or_b32 s8, s80, 31
	s_nop 0
	v_addc_co_u32_e32 v33, vcc, 0, v9, vcc
	global_load_ushort v31, v[32:33], off
	global_load_ushort v29, v[8:9], off offset:3072
	v_mad_u64_u32 v[8:9], s[78:79], s8, v195, v[4:5]
	v_add_co_u32_e32 v32, vcc, 0x1000, v8
	s_cmpk_eq_i32 s1, 0xfe0
	s_nop 0
	v_addc_co_u32_e32 v33, vcc, 0, v9, vcc
	global_load_ushort v33, v[32:33], off
	s_nop 0
	global_load_ushort v32, v[8:9], off offset:3072
	v_readlane_b32 s78, v251, 37
	v_readlane_b32 s79, v251, 38
	v_readlane_b32 vcc_lo, v255, 24
	s_nop 1
	v_add_u32_e32 v8, vcc_lo, v2
	v_ashrrev_i32_e32 v9, 31, v8
	v_lshl_add_u64 v[8:9], v[8:9], 2, s[78:79]
	global_load_dword v219, v[8:9], off
	v_lshlrev_b32_e32 v8, 2, v2
	s_add_u32 s78, s2, 0x0
	s_addc_u32 s79, s3, 0
	global_load_dword v208, v8, s[78:79]
	global_load_dword v209, v8, s[78:79] offset:2048
	s_add_u32 s78, s2, 0x1000
	s_addc_u32 s79, s3, 0
	global_load_dword v210, v8, s[78:79] offset:2048
	global_load_dword v211, v8, s[78:79]
	s_add_u32 s78, s2, 0x2000
	s_addc_u32 s79, s3, 0
	global_load_dword v212, v8, s[78:79]
	global_load_dword v213, v8, s[78:79] offset:2048
	s_add_u32 s78, s2, 0x3000
	s_addc_u32 s79, s3, 0
	global_load_dword v214, v8, s[78:79]
	s_add_u32 s78, s2, 0x4000
	s_addc_u32 s79, s3, 0
	global_load_dword v215, v8, s[78:79]
	global_load_dword v216, v8, s[78:79] offset:2048
	s_add_u32 s78, s2, 0x5000
	s_addc_u32 s79, s3, 0
	global_load_dword v217, v8, s[78:79]
	s_add_u32 s78, s2, 0x6000
	s_addc_u32 s79, s3, 0
	global_load_dword v218, v8, s[78:79]
	global_load_dword v220, v8, s[78:79] offset:2048
	s_add_u32 s78, s2, 0x7000
	s_addc_u32 s79, s3, 0
	global_load_dword v221, v8, s[78:79]
	s_add_u32 s78, s2, 0x8000
	s_addc_u32 s79, s3, 0
	global_load_dword v222, v8, s[78:79]
	global_load_dword v223, v8, s[78:79] offset:2048
	s_add_u32 s78, s2, 0x9000
	s_addc_u32 s79, s3, 0
	global_load_dword v224, v8, s[78:79]
	s_add_u32 s78, s2, 0xa000
	s_addc_u32 s79, s3, 0
	global_load_dword v225, v8, s[78:79]
	global_load_dword v226, v8, s[78:79] offset:2048
	s_add_u32 s78, s2, 0xb000
	s_addc_u32 s79, s3, 0
	global_load_dword v227, v8, s[78:79]
	s_add_u32 s78, s2, 0x3000
	s_addc_u32 s79, s3, 0
	global_load_dword v228, v8, s[78:79] offset:2048
	s_add_u32 s78, s2, 0x5000
	s_addc_u32 s79, s3, 0
	global_load_dword v229, v8, s[78:79] offset:2048
	s_add_u32 s78, s2, 0x7000
	s_addc_u32 s79, s3, 0
	global_load_dword v230, v8, s[78:79] offset:2048
	s_add_u32 s78, s2, 0x9000
	s_addc_u32 s79, s3, 0
	global_load_dword v231, v8, s[78:79] offset:2048
	s_add_u32 s78, s2, 0xb000
	s_addc_u32 s79, s3, 0
	global_load_dword v232, v8, s[78:79] offset:2048
	s_add_u32 s78, s2, 0xd000
	s_addc_u32 s79, s3, 0
	global_load_dword v233, v8, s[78:79] offset:2048
	s_add_u32 s78, s2, 0xc000
	s_addc_u32 s79, s3, 0
	global_load_dword v234, v8, s[78:79]
	global_load_dword v235, v8, s[78:79] offset:2048
	s_add_u32 s78, s2, 0xd000
	s_addc_u32 s79, s3, 0
	global_load_dword v236, v8, s[78:79]
	s_add_u32 s78, s2, 0xe000
	s_addc_u32 s79, s3, 0
	global_load_dword v237, v8, s[78:79]
	s_cmpk_eq_i32 s1, 0xfe0
	v_readlane_b32 s83, v255, 1
	v_readlane_b32 s84, v255, 2
	v_readlane_b32 s85, v255, 3
	v_readlane_b32 s86, v255, 4
	v_readlane_b32 s87, v255, 5
	v_readlane_b32 s88, v255, 6
	v_readlane_b32 s89, v255, 7
	v_readlane_b32 s90, v255, 8
	v_readlane_b32 s91, v255, 9
	v_readlane_b32 s92, v255, 10
	v_readlane_b32 s93, v255, 11
	v_readlane_b32 s94, v255, 12
	v_readlane_b32 s95, v255, 13
	s_cbranch_scc1 .LBB0_352
	v_lshlrev_b32_e32 v7, 16, v238
	v_mul_f32_e32 v7, 0xbfb8aa3b, v7
	v_exp_f32_e32 v7, v7
	v_lshlrev_b32_e32 v6, 16, v239
	v_add_f32_e32 v7, 1.0, v7
	v_div_scale_f32 v8, s[78:79], v7, v7, v6
	v_rcp_f32_e32 v9, v8
	v_div_scale_f32 v35, vcc, v6, v7, v6
	v_fma_f32 v39, -v8, v9, 1.0
	v_fmac_f32_e32 v9, v39, v9
	v_mul_f32_e32 v39, v35, v9
	v_fma_f32 v40, -v8, v39, v35
	v_fmac_f32_e32 v39, v40, v9
	v_fma_f32 v8, -v8, v39, v35
	v_div_fmas_f32 v8, v8, v9, v39
	v_div_fixup_f32 v6, v8, v7, v6
	v_mov_b32_e32 v7, 0
	s_cmpk_gt_u32 s1, 0xfde
	v_mov_b32_e32 v8, 0
	s_cbranch_scc0 .LBB0_353

; __device__ __forceinline__ void conv_tile(const Params& p, int l, int item, const bf16* PROJ, bf16* CV, LAS float* sl) {
;     ...
;     for (int rr = 0; rr < 62; ++rr) { const int sq = s0 - 15 + rr; const bool ok = sq >= 0 && sq < SEQ; const bf16* pr = PROJ + (size_t)(b * SEQ + (ok ? sq : s0)) * NIN;
;         const float a = bf2f(pr[PB_A + c]), g = bf2f(pr[PB_G + c]); u[rr] = ok ? a / (1.0f + __expf(-g)) : 0.f; }
.LBB0_345:
	s_waitcnt vmcnt(38)
	v_lshlrev_b32_e32 v4, 16, v102
	v_mul_f32_e32 v4, 0xbfb8aa3b, v4
	v_exp_f32_e32 v4, v4
	v_lshlrev_b32_e32 v5, 16, v101
	s_waitcnt vmcnt(38)
	v_lshlrev_b32_e32 v100, 16, v100
	v_mul_f32_e32 v100, 0xbfb8aa3b, v100
	v_add_f32_e32 v4, 1.0, v4
	v_div_scale_f32 v101, s[0:1], v4, v4, v5
	v_rcp_f32_e32 v102, v101
	v_exp_f32_e32 v100, v100
	v_div_scale_f32 v103, vcc, v5, v4, v5
	v_fma_f32 v104, -v101, v102, 1.0
	v_fmac_f32_e32 v102, v104, v102
	v_mul_f32_e32 v104, v103, v102
	v_fma_f32 v105, -v101, v104, v103
	v_fmac_f32_e32 v104, v105, v102
	s_waitcnt vmcnt(38)
	v_lshlrev_b32_e32 v99, 16, v99
	v_add_f32_e32 v100, 1.0, v100
	v_fma_f32 v101, -v101, v104, v103
	v_div_scale_f32 v103, s[0:1], v100, v100, v99
	v_rcp_f32_e32 v105, v103
	s_waitcnt vmcnt(37)
	v_lshlrev_b32_e32 v97, 16, v97
	v_mul_f32_e32 v97, 0xbfb8aa3b, v97
	v_div_fmas_f32 v101, v101, v102, v104
	v_exp_f32_e32 v97, v97
	v_div_fixup_f32 v121, v101, v4, v5
	v_fma_f32 v4, -v103, v105, 1.0
	v_fmac_f32_e32 v105, v4, v105
	v_div_scale_f32 v4, vcc, v99, v100, v99
	v_mul_f32_e32 v5, v4, v105
	v_fma_f32 v101, -v103, v5, v4
	s_waitcnt vmcnt(36)
	v_lshlrev_b32_e32 v30, 16, v30
	v_add_f32_e32 v97, 1.0, v97
	v_fmac_f32_e32 v5, v101, v105
	v_div_scale_f32 v101, s[0:1], v97, v97, v30
	v_rcp_f32_e32 v102, v101
	s_waitcnt vmcnt(36)
	v_lshlrev_b32_e32 v98, 16, v98
	v_fma_f32 v4, -v103, v5, v4
	v_mul_f32_e32 v98, 0xbfb8aa3b, v98
	v_div_fmas_f32 v4, v4, v105, v5
	v_exp_f32_e32 v98, v98
	v_div_fixup_f32 v119, v4, v100, v99
	v_fma_f32 v4, -v101, v102, 1.0
	v_fmac_f32_e32 v102, v4, v102
	v_div_scale_f32 v4, vcc, v30, v97, v30
	v_mul_f32_e32 v5, v4, v102
	v_fma_f32 v99, -v101, v5, v4
	s_waitcnt vmcnt(36)
	v_lshlrev_b32_e32 v96, 16, v96
	v_add_f32_e32 v98, 1.0, v98
	v_fmac_f32_e32 v5, v99, v102
	v_div_scale_f32 v99, s[0:1], v98, v98, v96
	v_rcp_f32_e32 v100, v99
	s_waitcnt vmcnt(36)
	v_lshlrev_b32_e32 v95, 16, v95
	v_fma_f32 v4, -v101, v5, v4
	v_mul_f32_e32 v95, 0xbfb8aa3b, v95
	v_div_fmas_f32 v4, v4, v102, v5
	v_exp_f32_e32 v95, v95
	v_div_fixup_f32 v30, v4, v97, v30
	v_fma_f32 v4, -v99, v100, 1.0
	v_fmac_f32_e32 v100, v4, v100
	v_div_scale_f32 v4, vcc, v96, v98, v96
	v_mul_f32_e32 v5, v4, v100
	v_fma_f32 v97, -v99, v5, v4
	s_waitcnt vmcnt(36)
	v_lshlrev_b32_e32 v94, 16, v94
	v_add_f32_e32 v95, 1.0, v95
	v_fmac_f32_e32 v5, v97, v100
	v_div_scale_f32 v97, s[0:1], v95, v95, v94
	v_fma_f32 v4, -v99, v5, v4
	v_rcp_f32_e32 v99, v97
	s_waitcnt vmcnt(36)
	v_lshlrev_b32_e32 v93, 16, v93
	v_div_fmas_f32 v4, v4, v100, v5
	v_mul_f32_e32 v93, 0xbfb8aa3b, v93
	v_div_fixup_f32 v111, v4, v98, v96
	v_fma_f32 v4, -v97, v99, 1.0
	v_exp_f32_e32 v93, v93
	v_fmac_f32_e32 v99, v4, v99
	v_div_scale_f32 v4, vcc, v94, v95, v94
	v_mul_f32_e32 v5, v4, v99
	v_fma_f32 v96, -v97, v5, v4
	v_fmac_f32_e32 v5, v96, v99
	s_waitcnt vmcnt(36)
	v_lshlrev_b32_e32 v96, 16, v91
	v_add_f32_e32 v93, 1.0, v93
	v_fma_f32 v4, -v97, v5, v4
	v_div_scale_f32 v97, s[0:1], v93, v93, v96
	v_rcp_f32_e32 v98, v97
	s_waitcnt vmcnt(36)
	v_lshlrev_b32_e32 v90, 16, v90
	v_div_fmas_f32 v4, v4, v99, v5
	v_mul_f32_e32 v90, 0xbfb8aa3b, v90
	v_div_fixup_f32 v91, v4, v95, v94
	v_fma_f32 v4, -v97, v98, 1.0
	v_exp_f32_e32 v90, v90
	v_fmac_f32_e32 v98, v4, v98
	v_div_scale_f32 v4, vcc, v96, v93, v96
	v_mul_f32_e32 v5, v4, v98
	v_fma_f32 v94, -v97, v5, v4
	v_fmac_f32_e32 v5, v94, v98
	s_waitcnt vmcnt(36)
	v_lshlrev_b32_e32 v81, 16, v81
	v_add_f32_e32 v94, 1.0, v90
	v_div_scale_f32 v95, s[0:1], v94, v94, v81
	v_fma_f32 v4, -v97, v5, v4
	v_rcp_f32_e32 v97, v95
	s_waitcnt vmcnt(36)
	v_lshlrev_b32_e32 v92, 16, v92
	v_mul_f32_e32 v92, 0xbfb8aa3b, v92
	v_div_fmas_f32 v4, v4, v98, v5
	v_exp_f32_e32 v92, v92
	v_div_fixup_f32 v90, v4, v93, v96
	v_fma_f32 v4, -v95, v97, 1.0
	v_fmac_f32_e32 v97, v4, v97
	v_div_scale_f32 v4, vcc, v81, v94, v81
	v_mul_f32_e32 v5, v4, v97
	v_fma_f32 v93, -v95, v5, v4
	s_waitcnt vmcnt(36)
	v_lshlrev_b32_e32 v89, 16, v89
	v_add_f32_e32 v92, 1.0, v92
	v_fmac_f32_e32 v5, v93, v97
	v_div_scale_f32 v93, s[0:1], v92, v92, v89
	v_fma_f32 v4, -v95, v5, v4
	v_rcp_f32_e32 v95, v93
	v_div_fmas_f32 v4, v4, v97, v5
	s_waitcnt vmcnt(36)
	v_lshlrev_b32_e32 v88, 16, v88
	v_div_fixup_f32 v81, v4, v94, v81
	v_fma_f32 v4, -v93, v95, 1.0
	v_mul_f32_e32 v88, 0xbfb8aa3b, v88
	v_fmac_f32_e32 v95, v4, v95
	v_div_scale_f32 v4, vcc, v89, v92, v89
	v_exp_f32_e32 v88, v88
	v_mul_f32_e32 v5, v4, v95
	v_fma_f32 v94, -v93, v5, v4
	v_fmac_f32_e32 v5, v94, v95
	v_fma_f32 v4, -v93, v5, v4
	s_waitcnt vmcnt(36)
	v_lshlrev_b32_e32 v93, 16, v77
	v_add_f32_e32 v88, 1.0, v88
	v_div_scale_f32 v94, s[0:1], v88, v88, v93
	v_rcp_f32_e32 v96, v94
	s_waitcnt vmcnt(36)
	v_lshlrev_b32_e32 v87, 16, v87
	v_div_fmas_f32 v4, v4, v95, v5
	v_mul_f32_e32 v87, 0xbfb8aa3b, v87
	v_div_fixup_f32 v77, v4, v92, v89
	v_fma_f32 v4, -v94, v96, 1.0
	v_exp_f32_e32 v87, v87
	v_fmac_f32_e32 v96, v4, v96
	v_div_scale_f32 v4, vcc, v93, v88, v93
	v_mul_f32_e32 v5, v4, v96
	v_fma_f32 v89, -v94, v5, v4
	v_fmac_f32_e32 v5, v89, v96
	s_waitcnt vmcnt(36)
	v_lshlrev_b32_e32 v89, 16, v76
	v_add_f32_e32 v87, 1.0, v87
	v_div_scale_f32 v92, s[0:1], v87, v87, v89
	v_fma_f32 v4, -v94, v5, v4
	v_rcp_f32_e32 v94, v92
	s_waitcnt vmcnt(36)
	v_lshlrev_b32_e32 v74, 16, v74
	v_div_fmas_f32 v4, v4, v96, v5
	v_mul_f32_e32 v74, 0xbfb8aa3b, v74
	v_div_fixup_f32 v76, v4, v88, v93
	v_fma_f32 v4, -v92, v94, 1.0
	v_exp_f32_e32 v74, v74
	v_fmac_f32_e32 v94, v4, v94
	v_div_scale_f32 v4, vcc, v89, v87, v89
	v_mul_f32_e32 v5, v4, v94
	v_fma_f32 v88, -v92, v5, v4
	v_fmac_f32_e32 v5, v88, v94
	s_waitcnt vmcnt(36)
	v_lshlrev_b32_e32 v71, 16, v71
	v_add_f32_e32 v88, 1.0, v74
	v_fma_f32 v4, -v92, v5, v4
	v_div_scale_f32 v92, s[0:1], v88, v88, v71
	v_rcp_f32_e32 v93, v92
	s_waitcnt vmcnt(36)
; __device__ __forceinline__ void conv_tile(const Params& p, int l, int item, const bf16* PROJ, bf16* CV, LAS float* sl) {
;     ...
;     for (int rr = 0; rr < 62; ++rr) { const int sq = s0 - 15 + rr; const bool ok = sq >= 0 && sq < SEQ; const bf16* pr = PROJ + (size_t)(b * SEQ + (ok ? sq : s0)) * NIN;
;         const float a = bf2f(pr[PB_A + c]), g = bf2f(pr[PB_G + c]); u[rr] = ok ? a / (1.0f + __expf(-g)) : 0.f; }
	v_lshlrev_b32_e32 v86, 16, v86
	v_mul_f32_e32 v86, 0xbfb8aa3b, v86
	v_div_fmas_f32 v4, v4, v94, v5
	v_exp_f32_e32 v86, v86
	v_div_fixup_f32 v74, v4, v87, v89
	v_fma_f32 v4, -v92, v93, 1.0
	v_fmac_f32_e32 v93, v4, v93
	v_div_scale_f32 v4, vcc, v71, v88, v71
	v_mul_f32_e32 v5, v4, v93
	v_fma_f32 v87, -v92, v5, v4
	s_waitcnt vmcnt(36)
	v_lshlrev_b32_e32 v85, 16, v85
	v_add_f32_e32 v86, 1.0, v86
	v_fmac_f32_e32 v5, v87, v93
	v_div_scale_f32 v87, s[0:1], v86, v86, v85
	v_rcp_f32_e32 v89, v87
	v_fma_f32 v4, -v92, v5, v4
	v_div_fmas_f32 v4, v4, v93, v5
	s_waitcnt vmcnt(36)
	v_lshlrev_b32_e32 v84, 16, v84
	v_div_fixup_f32 v71, v4, v88, v71
	v_fma_f32 v4, -v87, v89, 1.0
	v_mul_f32_e32 v84, 0xbfb8aa3b, v84
	v_fmac_f32_e32 v89, v4, v89
	v_div_scale_f32 v4, vcc, v85, v86, v85
	v_exp_f32_e32 v84, v84
	v_mul_f32_e32 v5, v4, v89
	v_fma_f32 v88, -v87, v5, v4
	v_fmac_f32_e32 v5, v88, v89
	v_fma_f32 v4, -v87, v5, v4
	s_waitcnt vmcnt(36)
	v_lshlrev_b32_e32 v87, 16, v69
	v_add_f32_e32 v84, 1.0, v84
	v_div_scale_f32 v88, s[0:1], v84, v84, v87
	v_rcp_f32_e32 v92, v88
	s_waitcnt vmcnt(36)
	v_lshlrev_b32_e32 v83, 16, v83
	v_div_fmas_f32 v4, v4, v89, v5
	v_mul_f32_e32 v83, 0xbfb8aa3b, v83
	v_div_fixup_f32 v69, v4, v86, v85
	v_fma_f32 v4, -v88, v92, 1.0
	v_exp_f32_e32 v83, v83
	v_fmac_f32_e32 v92, v4, v92
	v_div_scale_f32 v4, vcc, v87, v84, v87
	v_mul_f32_e32 v5, v4, v92
	v_fma_f32 v85, -v88, v5, v4
	v_fmac_f32_e32 v5, v85, v92
	s_waitcnt vmcnt(36)
	v_lshlrev_b32_e32 v85, 16, v66
	v_add_f32_e32 v83, 1.0, v83
	v_div_scale_f32 v86, s[0:1], v83, v83, v85
	v_fma_f32 v4, -v88, v5, v4
	v_rcp_f32_e32 v88, v86
	s_waitcnt vmcnt(36)
	v_lshlrev_b32_e32 v63, 16, v63
	v_div_fmas_f32 v4, v4, v92, v5
	v_mul_f32_e32 v63, 0xbfb8aa3b, v63
	v_div_fixup_f32 v66, v4, v84, v87
	v_fma_f32 v4, -v86, v88, 1.0
	v_exp_f32_e32 v63, v63
	v_fmac_f32_e32 v88, v4, v88
	v_div_scale_f32 v4, vcc, v85, v83, v85
	v_mul_f32_e32 v5, v4, v88
	v_fma_f32 v84, -v86, v5, v4
	v_fmac_f32_e32 v5, v84, v88
	s_waitcnt vmcnt(36)
	v_lshlrev_b32_e32 v61, 16, v61
	v_add_f32_e32 v84, 1.0, v63
	v_fma_f32 v4, -v86, v5, v4
	v_div_scale_f32 v86, s[0:1], v84, v84, v61
	v_rcp_f32_e32 v87, v86
	s_waitcnt vmcnt(36)
	v_lshlrev_b32_e32 v82, 16, v82
	v_mul_f32_e32 v82, 0xbfb8aa3b, v82
	v_div_fmas_f32 v4, v4, v88, v5
	v_exp_f32_e32 v82, v82
	v_div_fixup_f32 v63, v4, v83, v85
	v_fma_f32 v4, -v86, v87, 1.0
	v_fmac_f32_e32 v87, v4, v87
	v_div_scale_f32 v4, vcc, v61, v84, v61
	v_mul_f32_e32 v5, v4, v87
	v_fma_f32 v83, -v86, v5, v4
	s_waitcnt vmcnt(36)
	v_lshlrev_b32_e32 v80, 16, v80
	v_add_f32_e32 v82, 1.0, v82
	v_fmac_f32_e32 v5, v83, v87
	v_div_scale_f32 v83, s[0:1], v82, v82, v80
	v_rcp_f32_e32 v85, v83
	v_fma_f32 v4, -v86, v5, v4
	v_div_fmas_f32 v4, v4, v87, v5
	s_waitcnt vmcnt(36)
	v_lshlrev_b32_e32 v79, 16, v79
	v_div_fixup_f32 v61, v4, v84, v61
	v_fma_f32 v4, -v83, v85, 1.0
	v_mul_f32_e32 v79, 0xbfb8aa3b, v79
	v_fmac_f32_e32 v85, v4, v85
	v_div_scale_f32 v4, vcc, v80, v82, v80
	v_exp_f32_e32 v79, v79
	v_mul_f32_e32 v5, v4, v85
	v_fma_f32 v84, -v83, v5, v4
	v_fmac_f32_e32 v5, v84, v85
	v_fma_f32 v4, -v83, v5, v4
	s_waitcnt vmcnt(36)
	v_lshlrev_b32_e32 v83, 16, v58
	v_add_f32_e32 v79, 1.0, v79
	v_div_scale_f32 v84, s[0:1], v79, v79, v83
	v_rcp_f32_e32 v86, v84
	s_waitcnt vmcnt(36)
	v_lshlrev_b32_e32 v78, 16, v78
	v_div_fmas_f32 v4, v4, v85, v5
	v_mul_f32_e32 v78, 0xbfb8aa3b, v78
	v_div_fixup_f32 v58, v4, v82, v80
	v_fma_f32 v4, -v84, v86, 1.0
	v_exp_f32_e32 v78, v78
	v_fmac_f32_e32 v86, v4, v86
	v_div_scale_f32 v4, vcc, v83, v79, v83
	v_mul_f32_e32 v5, v4, v86
	v_fma_f32 v80, -v84, v5, v4
	v_fmac_f32_e32 v5, v80, v86
	s_waitcnt vmcnt(36)
	v_lshlrev_b32_e32 v80, 16, v56
	v_add_f32_e32 v78, 1.0, v78
	v_div_scale_f32 v82, s[0:1], v78, v78, v80
	v_fma_f32 v4, -v84, v5, v4
	v_rcp_f32_e32 v84, v82
	s_waitcnt vmcnt(36)
	v_lshlrev_b32_e32 v73, 16, v73
	v_div_fmas_f32 v4, v4, v86, v5
	v_mul_f32_e32 v73, 0xbfb8aa3b, v73
	v_div_fixup_f32 v56, v4, v79, v83
	v_fma_f32 v4, -v82, v84, 1.0
	v_exp_f32_e32 v73, v73
	v_fmac_f32_e32 v84, v4, v84
	v_div_scale_f32 v4, vcc, v80, v78, v80
	v_mul_f32_e32 v5, v4, v84
	v_fma_f32 v79, -v82, v5, v4
	v_fmac_f32_e32 v5, v79, v84
	s_waitcnt vmcnt(36)
	v_lshlrev_b32_e32 v79, 16, v57
	v_add_f32_e32 v73, 1.0, v73
	v_fma_f32 v4, -v82, v5, v4
	v_div_scale_f32 v82, s[0:1], v73, v73, v79
	v_rcp_f32_e32 v83, v82
	s_waitcnt vmcnt(36)
	v_lshlrev_b32_e32 v75, 16, v75
	v_div_fmas_f32 v4, v4, v84, v5
	v_mul_f32_e32 v75, 0xbfb8aa3b, v75
	v_div_fixup_f32 v57, v4, v78, v80
	v_fma_f32 v4, -v82, v83, 1.0
	v_exp_f32_e32 v75, v75
	v_fmac_f32_e32 v83, v4, v83
	v_div_scale_f32 v4, vcc, v79, v73, v79
	v_mul_f32_e32 v5, v4, v83
	v_fma_f32 v78, -v82, v5, v4
	v_fmac_f32_e32 v5, v78, v83
	s_waitcnt vmcnt(36)
	v_lshlrev_b32_e32 v78, 16, v59
	v_add_f32_e32 v75, 1.0, v75
	v_div_scale_f32 v80, s[0:1], v75, v75, v78
	v_fma_f32 v4, -v82, v5, v4
	v_rcp_f32_e32 v82, v80
	s_waitcnt vmcnt(36)
	v_lshlrev_b32_e32 v72, 16, v72
	v_div_fmas_f32 v4, v4, v83, v5
	v_mul_f32_e32 v72, 0xbfb8aa3b, v72
	v_div_fixup_f32 v59, v4, v73, v79
	v_fma_f32 v4, -v80, v82, 1.0
	v_exp_f32_e32 v72, v72
	v_fmac_f32_e32 v82, v4, v82
	v_div_scale_f32 v4, vcc, v78, v75, v78
	v_mul_f32_e32 v5, v4, v82
	v_fma_f32 v73, -v80, v5, v4
	v_fmac_f32_e32 v5, v73, v82
	s_waitcnt vmcnt(36)
	v_lshlrev_b32_e32 v73, 16, v60
	v_add_f32_e32 v72, 1.0, v72
	v_div_scale_f32 v79, s[0:1], v72, v72, v73
	v_fma_f32 v4, -v80, v5, v4
	v_rcp_f32_e32 v80, v79
	s_waitcnt vmcnt(36)
	v_lshlrev_b32_e32 v70, 16, v70
	v_div_fmas_f32 v4, v4, v82, v5
	v_mul_f32_e32 v70, 0xbfb8aa3b, v70
	v_div_fixup_f32 v60, v4, v75, v78
	v_fma_f32 v4, -v79, v80, 1.0
	v_exp_f32_e32 v70, v70
	v_fmac_f32_e32 v80, v4, v80
	v_div_scale_f32 v4, vcc, v73, v72, v73
	v_mul_f32_e32 v5, v4, v80
	v_fma_f32 v75, -v79, v5, v4
	v_fmac_f32_e32 v5, v75, v80
	s_waitcnt vmcnt(36)
; __device__ __forceinline__ void conv_tile(const Params& p, int l, int item, const bf16* PROJ, bf16* CV, LAS float* sl) {
;     ...
;     for (int rr = 0; rr < 62; ++rr) { const int sq = s0 - 15 + rr; const bool ok = sq >= 0 && sq < SEQ; const bf16* pr = PROJ + (size_t)(b * SEQ + (ok ? sq : s0)) * NIN;
;         const float a = bf2f(pr[PB_A + c]), g = bf2f(pr[PB_G + c]); u[rr] = ok ? a / (1.0f + __expf(-g)) : 0.f; }
;     float w[31];
; #pragma unroll
;     for (int j = 0; j < 31; ++j) w[j] = p.conv_dw[(size_t)(l * 31 + j) * CC + c];
	v_lshlrev_b32_e32 v75, 16, v62
	v_add_f32_e32 v70, 1.0, v70
	v_div_scale_f32 v78, s[0:1], v70, v70, v75
	v_fma_f32 v4, -v79, v5, v4
	v_rcp_f32_e32 v79, v78
	s_waitcnt vmcnt(36)
	v_lshlrev_b32_e32 v67, 16, v67
	v_div_fmas_f32 v4, v4, v80, v5
	v_mul_f32_e32 v67, 0xbfb8aa3b, v67
	v_div_fixup_f32 v62, v4, v72, v73
	v_fma_f32 v4, -v78, v79, 1.0
	v_exp_f32_e32 v67, v67
	v_fmac_f32_e32 v79, v4, v79
	v_div_scale_f32 v4, vcc, v75, v70, v75
	v_mul_f32_e32 v5, v4, v79
	v_fma_f32 v72, -v78, v5, v4
	v_fmac_f32_e32 v5, v72, v79
	s_waitcnt vmcnt(36)
	v_lshlrev_b32_e32 v72, 16, v64
	v_add_f32_e32 v67, 1.0, v67
	v_div_scale_f32 v73, s[0:1], v67, v67, v72
	v_fma_f32 v4, -v78, v5, v4
	v_rcp_f32_e32 v78, v73
	s_waitcnt vmcnt(36)
	v_lshlrev_b32_e32 v68, 16, v68
	v_div_fmas_f32 v4, v4, v79, v5
	v_mul_f32_e32 v68, 0xbfb8aa3b, v68
	v_div_fixup_f32 v64, v4, v70, v75
	v_fma_f32 v4, -v73, v78, 1.0
	v_exp_f32_e32 v68, v68
	v_fmac_f32_e32 v78, v4, v78
	v_div_scale_f32 v4, vcc, v72, v67, v72
	v_mul_f32_e32 v5, v4, v78
	v_fma_f32 v70, -v73, v5, v4
	v_fmac_f32_e32 v5, v70, v78
	s_waitcnt vmcnt(36)
	v_lshlrev_b32_e32 v70, 16, v65
	v_add_f32_e32 v68, 1.0, v68
	v_fma_f32 v4, -v73, v5, v4
	v_div_scale_f32 v73, s[0:1], v68, v68, v70
	v_rcp_f32_e32 v75, v73
	s_waitcnt vmcnt(36)
	v_lshlrev_b32_e32 v55, 16, v55
	v_mul_f32_e32 v55, 0xbfb8aa3b, v55
	v_div_fmas_f32 v4, v4, v78, v5
	v_exp_f32_e32 v55, v55
	v_div_fixup_f32 v65, v4, v67, v72
	v_fma_f32 v4, -v73, v75, 1.0
	v_fmac_f32_e32 v75, v4, v75
	v_div_scale_f32 v4, vcc, v70, v68, v70
	v_mul_f32_e32 v5, v4, v75
	v_fma_f32 v67, -v73, v5, v4
	s_waitcnt vmcnt(36)
	v_lshlrev_b32_e32 v54, 16, v54
	v_add_f32_e32 v55, 1.0, v55
	v_fmac_f32_e32 v5, v67, v75
	v_div_scale_f32 v72, s[0:1], v55, v55, v54
	v_fma_f32 v4, -v73, v5, v4
	v_rcp_f32_e32 v73, v72
	s_waitcnt vmcnt(36)
	v_lshlrev_b32_e32 v53, 16, v53
	v_mul_f32_e32 v53, 0xbfb8aa3b, v53
	v_div_fmas_f32 v4, v4, v75, v5
	v_exp_f32_e32 v53, v53
	v_div_fixup_f32 v67, v4, v68, v70
	v_fma_f32 v4, -v72, v73, 1.0
	v_fmac_f32_e32 v73, v4, v73
	v_div_scale_f32 v4, vcc, v54, v55, v54
	v_mul_f32_e32 v5, v4, v73
	v_fma_f32 v68, -v72, v5, v4
	s_waitcnt vmcnt(36)
	v_lshlrev_b32_e32 v52, 16, v52
	v_add_f32_e32 v53, 1.0, v53
	v_fmac_f32_e32 v5, v68, v73
	v_div_scale_f32 v70, s[0:1], v53, v53, v52
	v_fma_f32 v4, -v72, v5, v4
	v_rcp_f32_e32 v72, v70
	s_waitcnt vmcnt(36)
	v_lshlrev_b32_e32 v44, 16, v44
	v_mul_f32_e32 v44, 0xbfb8aa3b, v44
	v_div_fmas_f32 v4, v4, v73, v5
	v_exp_f32_e32 v44, v44
	v_div_fixup_f32 v68, v4, v55, v54
	v_fma_f32 v4, -v70, v72, 1.0
	v_fmac_f32_e32 v72, v4, v72
	v_div_scale_f32 v4, vcc, v52, v53, v52
	v_mul_f32_e32 v5, v4, v72
	v_fma_f32 v54, -v70, v5, v4
	s_waitcnt vmcnt(36)
	v_lshlrev_b32_e32 v38, 16, v38
	v_add_f32_e32 v44, 1.0, v44
	v_fmac_f32_e32 v5, v54, v72
	v_div_scale_f32 v54, s[0:1], v44, v44, v38
	v_rcp_f32_e32 v55, v54
	s_waitcnt vmcnt(36)
	v_lshlrev_b32_e32 v47, 16, v47
	v_fma_f32 v4, -v70, v5, v4
	v_mul_f32_e32 v47, 0xbfb8aa3b, v47
	v_div_fmas_f32 v4, v4, v72, v5
	v_exp_f32_e32 v47, v47
	v_div_fixup_f32 v70, v4, v53, v52
	v_fma_f32 v4, -v54, v55, 1.0
	v_fmac_f32_e32 v55, v4, v55
	v_div_scale_f32 v4, vcc, v38, v44, v38
	v_mul_f32_e32 v5, v4, v55
	v_fma_f32 v52, -v54, v5, v4
	s_waitcnt vmcnt(36)
	v_lshlrev_b32_e32 v41, 16, v41
	v_add_f32_e32 v47, 1.0, v47
	v_fmac_f32_e32 v5, v52, v55
	v_div_scale_f32 v52, s[0:1], v47, v47, v41
	v_rcp_f32_e32 v53, v52
	s_waitcnt vmcnt(36)
	v_lshlrev_b32_e32 v37, 16, v37
	v_fma_f32 v4, -v54, v5, v4
	v_mul_f32_e32 v37, 0xbfb8aa3b, v37
	v_div_fmas_f32 v4, v4, v55, v5
	v_exp_f32_e32 v37, v37
	v_div_fixup_f32 v72, v4, v44, v38
	v_fma_f32 v4, -v52, v53, 1.0
	v_fmac_f32_e32 v53, v4, v53
	v_div_scale_f32 v4, vcc, v41, v47, v41
	v_mul_f32_e32 v5, v4, v53
	v_fma_f32 v38, -v52, v5, v4
	s_waitcnt vmcnt(36)
	v_lshlrev_b32_e32 v36, 16, v36
	v_add_f32_e32 v37, 1.0, v37
	v_fmac_f32_e32 v5, v38, v53
	v_div_scale_f32 v38, s[0:1], v37, v37, v36
	v_rcp_f32_e32 v44, v38
	v_fma_f32 v4, -v52, v5, v4
	v_div_fmas_f32 v4, v4, v53, v5
	s_waitcnt vmcnt(35)
	v_lshlrev_b32_e32 v34, 16, v34
	v_div_fixup_f32 v73, v4, v47, v41
	v_fma_f32 v4, -v38, v44, 1.0
	v_mul_f32_e32 v34, 0xbfb8aa3b, v34
	v_fmac_f32_e32 v44, v4, v44
	v_div_scale_f32 v4, vcc, v36, v37, v36
	v_exp_f32_e32 v34, v34
	v_mul_f32_e32 v5, v4, v44
	v_fma_f32 v41, -v38, v5, v4
	v_fmac_f32_e32 v5, v41, v44
	v_fma_f32 v4, -v38, v5, v4
	s_waitcnt vmcnt(34)
	v_lshlrev_b32_e32 v38, 16, v13
	v_add_f32_e32 v34, 1.0, v34
	v_div_scale_f32 v41, s[0:1], v34, v34, v38
	v_div_fmas_f32 v4, v4, v44, v5
	v_div_fixup_f32 v75, v4, v37, v36
	v_lshl_add_u64 v[36:37], v[2:3], 2, s[2:3]
	s_movk_i32 s0, 0x1000
	v_add_co_u32_e32 v4, vcc, s0, v36
	s_movk_i32 s0, 0x2000
	s_nop 0
	v_addc_co_u32_e32 v5, vcc, 0, v37, vcc
	v_add_co_u32_e32 v52, vcc, s0, v36
	s_movk_i32 s0, 0x3000
	s_nop 0
	v_addc_co_u32_e32 v53, vcc, 0, v37, vcc
	v_add_co_u32_e32 v54, vcc, s0, v36
	s_movk_i32 s0, 0x4000
	s_nop 0
	v_addc_co_u32_e32 v55, vcc, 0, v37, vcc
	s_waitcnt vmcnt(0)
; __device__ __forceinline__ void conv_tile(const Params& p, int l, int item, const bf16* PROJ, bf16* CV, LAS float* sl) {
;     ...
;         const float a = bf2f(pr[PB_A + c]), g = bf2f(pr[PB_G + c]); u[rr] = ok ? a / (1.0f + __expf(-g)) : 0.f; }
;     float w[31];
; #pragma unroll
;     for (int j = 0; j < 31; ++j) w[j] = p.conv_dw[(size_t)(l * 31 + j) * CC + c];
;     const float bias = p.conv_dw_b[l * CC + c];
;     float y[32], y2[32];
; #pragma unroll
;     for (int t = 0; t < 32; ++t) { float acc = bias;
; #pragma unroll
;         for (int j = 0; j < 31; ++j) acc = fmaf(u[t + j], w[j], acc);
;         y[t] = acc; y2[t] = acc * acc; }
	v_mov_b32_e32 v80, v208
	v_mov_b32_e32 v79, v209
	v_mov_b32_e32 v78, v210
	v_add_co_u32_e32 v4, vcc, s0, v36
	s_movk_i32 s0, 0x5000
	s_nop 0
	v_addc_co_u32_e32 v5, vcc, 0, v37, vcc
	v_add_co_u32_e32 v96, vcc, s0, v36
	s_movk_i32 s0, 0x6000
	s_nop 0
	v_addc_co_u32_e32 v97, vcc, 0, v37, vcc
	v_add_co_u32_e32 v92, vcc, s0, v36
	s_movk_i32 s0, 0x7000
	s_nop 0
	v_addc_co_u32_e32 v93, vcc, 0, v37, vcc
	v_mov_b32_e32 v89, v211
	v_mov_b32_e32 v88, v212
	v_mov_b32_e32 v87, v213
	v_mov_b32_e32 v86, v214
	v_mov_b32_e32 v84, v215
	v_mov_b32_e32 v83, v216
	v_mov_b32_e32 v85, v217
	v_mov_b32_e32 v82, v218
	v_add_co_u32_e32 v52, vcc, s0, v36
	s_mov_b32 s0, 0x8000
	s_nop 0
	v_addc_co_u32_e32 v53, vcc, 0, v37, vcc
	v_add_co_u32_e32 v94, vcc, s0, v36
	s_mov_b32 s0, 0x9000
	s_nop 0
	v_addc_co_u32_e32 v95, vcc, 0, v37, vcc
	v_add_co_u32_e32 v114, vcc, s0, v36
	s_mov_b32 s0, 0xa000
	s_nop 0
	v_addc_co_u32_e32 v115, vcc, 0, v37, vcc
	v_add_co_u32_e32 v108, vcc, s0, v36
	s_mov_b32 s0, 0xb000
	s_nop 0
	v_addc_co_u32_e32 v109, vcc, 0, v37, vcc
	v_add_co_u32_e32 v116, vcc, s0, v36
	s_mov_b32 s0, 0xc000
	s_nop 0
	v_addc_co_u32_e32 v117, vcc, 0, v37, vcc
	v_add_co_u32_e32 v122, vcc, s0, v36
	v_readlane_b32 s0, v255, 24
	v_readlane_b32 s80, v251, 33
	v_readlane_b32 s84, v251, 37
	v_add_u32_e32 v4, s0, v2
	v_ashrrev_i32_e32 v5, 31, v4
	v_readlane_b32 s85, v251, 38
	v_addc_co_u32_e32 v123, vcc, 0, v37, vcc
	s_nop 0
	v_lshl_add_u64 v[98:99], v[4:5], 2, s[84:85]
	v_mov_b32_e32 v13, v219
	v_mov_b32_e32 v107, v220
	v_mov_b32_e32 v105, v221
	v_mov_b32_e32 v102, v222
	v_mov_b32_e32 v101, v223
	s_nop 0
	v_mov_b32_e32 v98, v224
	v_mov_b32_e32 v94, v225
	v_mov_b32_e32 v93, v226
	v_mov_b32_e32 v92, v227
	v_mov_b32_e32 v112, v228
	v_mov_b32_e32 v110, v229
	s_nop 0
	v_mov_b32_e32 v109, v230
	v_mov_b32_e32 v108, v231
	v_mov_b32_e32 v96, v232
	s_mov_b32 s0, 0xd000
	v_add_co_u32_e32 v52, vcc, s0, v36
	s_mov_b32 s0, 0xe000
	s_nop 0
	v_addc_co_u32_e32 v53, vcc, 0, v37, vcc
	v_add_co_u32_e32 v54, vcc, s0, v36
	s_mov_b32 s0, 0xf000
	s_nop 0
	v_addc_co_u32_e32 v55, vcc, 0, v37, vcc
	v_mov_b32_e32 v95, v233
	v_mov_b32_e32 v106, v234
	v_mov_b32_e32 v104, v235
	v_mov_b32_e32 v103, v236
	v_mov_b32_e32 v99, v237
	global_load_dword v97, v[54:55], off offset:2048
	v_add_co_u32_e32 v36, vcc, s0, v36
	v_rcp_f32_e32 v47, v41
	s_nop 0
	v_addc_co_u32_e32 v37, vcc, 0, v37, vcc
	global_load_dword v100, v[36:37], off
	s_waitcnt vmcnt(35)
	v_lshlrev_b32_e32 v31, 16, v31
	v_mul_f32_e32 v31, 0xbfb8aa3b, v31
	v_fma_f32 v44, -v41, v47, 1.0
	v_exp_f32_e32 v31, v31
	v_fmac_f32_e32 v47, v44, v47
	v_div_scale_f32 v36, vcc, v38, v34, v38
	v_mul_f32_e32 v37, v36, v47
	v_fma_f32 v44, -v41, v37, v36
	v_readlane_b32 s1, v255, 25
	v_fmac_f32_e32 v37, v44, v47
	s_waitcnt vmcnt(34)
	v_lshlrev_b32_e32 v29, 16, v29
	v_add_f32_e32 v31, 1.0, v31
	v_fma_f32 v36, -v41, v37, v36
	v_div_scale_f32 v41, s[0:1], v31, v31, v29
	v_rcp_f32_e32 v44, v41
	s_waitcnt vmcnt(33)
	v_lshlrev_b32_e32 v33, 16, v33
	v_mul_f32_e32 v33, 0xbfb8aa3b, v33
	v_div_fmas_f32 v36, v36, v47, v37
	v_exp_f32_e32 v33, v33
	v_div_fixup_f32 v115, v36, v34, v38
	v_fma_f32 v34, -v41, v44, 1.0
	v_fmac_f32_e32 v44, v34, v44
	v_div_scale_f32 v34, vcc, v29, v31, v29
	v_mul_f32_e32 v36, v34, v44
	v_fma_f32 v37, -v41, v36, v34
	s_waitcnt vmcnt(32)
	v_lshlrev_b32_e32 v32, 16, v32
	v_add_f32_e32 v33, 1.0, v33
	v_fmac_f32_e32 v36, v37, v44
	v_div_scale_f32 v37, s[0:1], v33, v33, v32
	v_rcp_f32_e32 v38, v37
	v_fma_f32 v34, -v41, v36, v34
	v_div_fmas_f32 v34, v34, v44, v36
	v_div_fixup_f32 v116, v34, v31, v29
	v_fma_f32 v29, -v37, v38, 1.0
	v_fmac_f32_e32 v38, v29, v38
	v_div_scale_f32 v29, vcc, v32, v33, v32
	v_mul_f32_e32 v31, v29, v38
	v_fma_f32 v34, -v37, v31, v29
	v_fmac_f32_e32 v31, v34, v38
	v_fma_f32 v29, -v37, v31, v29
	v_div_fmas_f32 v29, v29, v38, v31
	v_div_fixup_f32 v117, v29, v33, v32
	v_and_b32_e32 v114, 32, v2
	s_waitcnt vmcnt(20)
	v_fma_f32 v55, v28, v80, v13
	v_fmac_f32_e32 v55, v26, v79
	v_fma_f32 v54, v26, v80, v13
	v_fmac_f32_e32 v55, v27, v89
	v_fmac_f32_e32 v54, v27, v79
	v_fma_f32 v53, v27, v80, v13
	v_fmac_f32_e32 v55, v24, v78
	v_fmac_f32_e32 v54, v24, v89
	v_fmac_f32_e32 v53, v24, v79
	v_fma_f32 v52, v24, v80, v13
	v_fmac_f32_e32 v55, v25, v88
	v_fmac_f32_e32 v54, v25, v78
	v_fmac_f32_e32 v53, v25, v89
	v_fmac_f32_e32 v52, v25, v79
	v_fma_f32 v44, v25, v80, v13
	v_fmac_f32_e32 v55, v22, v87
	v_fmac_f32_e32 v54, v22, v88
	v_fmac_f32_e32 v53, v22, v78
	v_fmac_f32_e32 v52, v22, v89
	v_fmac_f32_e32 v44, v22, v79
	v_fma_f32 v47, v22, v80, v13
	v_fmac_f32_e32 v55, v23, v86
	v_fmac_f32_e32 v54, v23, v87
	v_fmac_f32_e32 v53, v23, v88
	v_fmac_f32_e32 v52, v23, v78
	v_fmac_f32_e32 v44, v23, v89
	v_fmac_f32_e32 v47, v23, v79
	v_fma_f32 v36, v23, v80, v13
	s_waitcnt vmcnt(11)
	v_fmac_f32_e32 v55, v20, v112
	v_fmac_f32_e32 v54, v20, v86
	v_fmac_f32_e32 v53, v20, v87
	v_fmac_f32_e32 v52, v20, v88
	v_fmac_f32_e32 v44, v20, v78
	v_fmac_f32_e32 v47, v20, v89
	v_fmac_f32_e32 v36, v20, v79
	v_fma_f32 v37, v20, v80, v13
	v_fmac_f32_e32 v55, v21, v84
	v_fmac_f32_e32 v54, v21, v112
	v_fmac_f32_e32 v53, v21, v86
	v_fmac_f32_e32 v52, v21, v87
	v_fmac_f32_e32 v44, v21, v88
	v_fmac_f32_e32 v47, v21, v78
	v_fmac_f32_e32 v36, v21, v89
	v_fmac_f32_e32 v37, v21, v79
	v_fma_f32 v38, v21, v80, v13
	v_fmac_f32_e32 v55, v18, v83
	v_fmac_f32_e32 v54, v18, v84
	v_fmac_f32_e32 v53, v18, v112
	v_fmac_f32_e32 v52, v18, v86
	v_fmac_f32_e32 v44, v18, v87
	v_fmac_f32_e32 v47, v18, v88
	v_fmac_f32_e32 v36, v18, v78
	v_fmac_f32_e32 v37, v18, v89
	v_fmac_f32_e32 v38, v18, v79
	v_fma_f32 v41, v18, v80, v13
	v_fmac_f32_e32 v55, v19, v85
	v_fmac_f32_e32 v54, v19, v83
	v_fmac_f32_e32 v53, v19, v84
	v_fmac_f32_e32 v52, v19, v112
	v_fmac_f32_e32 v44, v19, v86
	v_fmac_f32_e32 v47, v19, v87
	v_fmac_f32_e32 v36, v19, v88
	v_fmac_f32_e32 v37, v19, v78
	v_fmac_f32_e32 v38, v19, v89
	v_fmac_f32_e32 v41, v19, v79
	v_fma_f32 v34, v19, v80, v13
	s_waitcnt vmcnt(10)
; __device__ __forceinline__ void conv_tile(const Params& p, int l, int item, const bf16* PROJ, bf16* CV, LAS float* sl) {
;     ...
;     for (int t = 0; t < 32; ++t) { float acc = bias;
; #pragma unroll
;         for (int j = 0; j < 31; ++j) acc = fmaf(u[t + j], w[j], acc);
;         y[t] = acc; y2[t] = acc * acc; }
	v_fmac_f32_e32 v55, v16, v110
	v_fmac_f32_e32 v54, v16, v85
	v_fmac_f32_e32 v53, v16, v83
	v_fmac_f32_e32 v52, v16, v84
	v_fmac_f32_e32 v44, v16, v112
	v_fmac_f32_e32 v47, v16, v86
	v_fmac_f32_e32 v36, v16, v87
	v_fmac_f32_e32 v37, v16, v88
	v_fmac_f32_e32 v38, v16, v78
	v_fmac_f32_e32 v41, v16, v89
	v_fmac_f32_e32 v34, v16, v79
	v_fma_f32 v32, v16, v80, v13
	v_fmac_f32_e32 v55, v17, v82
	v_fmac_f32_e32 v54, v17, v110
	v_fmac_f32_e32 v53, v17, v85
	v_fmac_f32_e32 v52, v17, v83
	v_fmac_f32_e32 v44, v17, v84
	v_fmac_f32_e32 v47, v17, v112
	v_fmac_f32_e32 v36, v17, v86
	v_fmac_f32_e32 v37, v17, v87
	v_fmac_f32_e32 v38, v17, v88
	v_fmac_f32_e32 v41, v17, v78
	v_fmac_f32_e32 v34, v17, v89
	v_fmac_f32_e32 v32, v17, v79
	v_fma_f32 v31, v17, v80, v13
	v_fmac_f32_e32 v55, v14, v107
	v_fmac_f32_e32 v54, v14, v82
	v_fmac_f32_e32 v53, v14, v110
	v_fmac_f32_e32 v52, v14, v85
	v_fmac_f32_e32 v44, v14, v83
	v_fmac_f32_e32 v47, v14, v84
	v_fmac_f32_e32 v36, v14, v112
	v_fmac_f32_e32 v37, v14, v86
	v_fmac_f32_e32 v38, v14, v87
	v_fmac_f32_e32 v41, v14, v88
	v_fmac_f32_e32 v34, v14, v78
	v_fmac_f32_e32 v32, v14, v89
	v_fmac_f32_e32 v31, v14, v79
	v_fma_f32 v33, v14, v80, v13
	v_fmac_f32_e32 v55, v15, v105
	v_fmac_f32_e32 v54, v15, v107
	v_fmac_f32_e32 v53, v15, v82
	v_fmac_f32_e32 v52, v15, v110
	v_fmac_f32_e32 v44, v15, v85
	v_fmac_f32_e32 v47, v15, v83
	v_fmac_f32_e32 v36, v15, v84
	v_fmac_f32_e32 v37, v15, v112
	v_fmac_f32_e32 v38, v15, v86
	v_fmac_f32_e32 v41, v15, v87
	v_fmac_f32_e32 v34, v15, v88
	v_fmac_f32_e32 v32, v15, v78
	v_fmac_f32_e32 v31, v15, v89
	v_fmac_f32_e32 v33, v15, v79
	v_fma_f32 v29, v15, v80, v13
	s_waitcnt vmcnt(9)
	v_fmac_f32_e32 v55, v121, v109
	v_fmac_f32_e32 v54, v121, v105
	v_fmac_f32_e32 v53, v121, v107
	v_fmac_f32_e32 v52, v121, v82
	v_fmac_f32_e32 v44, v121, v110
	v_fmac_f32_e32 v47, v121, v85
	v_fmac_f32_e32 v36, v121, v83
	v_fmac_f32_e32 v37, v121, v84
	v_fmac_f32_e32 v38, v121, v112
	v_fmac_f32_e32 v41, v121, v86
	v_fmac_f32_e32 v34, v121, v87
	v_fmac_f32_e32 v32, v121, v88
	v_fmac_f32_e32 v31, v121, v78
	v_fmac_f32_e32 v33, v121, v89
	v_fmac_f32_e32 v29, v121, v79
	v_fma_f32 v28, v121, v80, v13
	v_fmac_f32_e32 v55, v119, v102
	v_fmac_f32_e32 v54, v119, v109
	v_fmac_f32_e32 v53, v119, v105
	v_fmac_f32_e32 v52, v119, v107
	v_fmac_f32_e32 v44, v119, v82
	v_fmac_f32_e32 v47, v119, v110
	v_fmac_f32_e32 v36, v119, v85
	v_fmac_f32_e32 v37, v119, v83
	v_fmac_f32_e32 v38, v119, v84
	v_fmac_f32_e32 v41, v119, v112
	v_fmac_f32_e32 v34, v119, v86
	v_fmac_f32_e32 v32, v119, v87
	v_fmac_f32_e32 v31, v119, v88
	v_fmac_f32_e32 v33, v119, v78
	v_fmac_f32_e32 v29, v119, v89
	v_fmac_f32_e32 v28, v119, v79
	v_fma_f32 v27, v119, v80, v13
	v_fmac_f32_e32 v55, v30, v101
	v_fmac_f32_e32 v54, v30, v102
	v_fmac_f32_e32 v53, v30, v109
	v_fmac_f32_e32 v52, v30, v105
	v_fmac_f32_e32 v44, v30, v107
	v_fmac_f32_e32 v47, v30, v82
	v_fmac_f32_e32 v36, v30, v110
	v_fmac_f32_e32 v37, v30, v85
	v_fmac_f32_e32 v38, v30, v83
	v_fmac_f32_e32 v41, v30, v84
	v_fmac_f32_e32 v34, v30, v112
	v_fmac_f32_e32 v32, v30, v86
	v_fmac_f32_e32 v31, v30, v87
	v_fmac_f32_e32 v33, v30, v88
	v_fmac_f32_e32 v29, v30, v78
	v_fmac_f32_e32 v28, v30, v89
	v_fmac_f32_e32 v27, v30, v79
	v_fma_f32 v30, v30, v80, v13
	v_fmac_f32_e32 v30, v111, v79
	v_fma_f32 v25, v111, v80, v13
	v_fma_f32 v24, v91, v80, v13
	v_fmac_f32_e32 v30, v91, v89
	v_fmac_f32_e32 v25, v91, v79
	v_fmac_f32_e32 v24, v90, v79
	v_fma_f32 v23, v90, v80, v13
	v_fmac_f32_e32 v30, v90, v78
	v_fmac_f32_e32 v25, v90, v89
	v_fmac_f32_e32 v24, v81, v89
	v_fmac_f32_e32 v23, v81, v79
	v_fma_f32 v26, v81, v80, v13
	v_fma_f32 v22, v71, v80, v13
	v_fmac_f32_e32 v30, v81, v88
	v_fmac_f32_e32 v25, v81, v78
	v_fmac_f32_e32 v24, v77, v78
	v_fmac_f32_e32 v23, v77, v89
	v_fmac_f32_e32 v26, v77, v79
	v_fma_f32 v21, v77, v80, v13
	v_fmac_f32_e32 v22, v69, v79
	v_fma_f32 v17, v69, v80, v13
	v_fma_f32 v18, v61, v80, v13
	v_fmac_f32_e32 v30, v77, v87
	v_fmac_f32_e32 v25, v77, v88
	v_fmac_f32_e32 v24, v76, v88
	v_fmac_f32_e32 v23, v76, v78
	v_fmac_f32_e32 v26, v76, v89
	v_fmac_f32_e32 v21, v76, v79
	v_fma_f32 v20, v76, v80, v13
	v_fma_f32 v19, v74, v80, v13
	v_fmac_f32_e32 v22, v66, v89
	v_fmac_f32_e32 v17, v66, v79
	v_fma_f32 v16, v66, v80, v13
	v_fma_f32 v15, v63, v80, v13
	v_fmac_f32_e32 v18, v58, v79
	v_fma_f32 v14, v58, v80, v13
	v_fmac_f32_e32 v13, v56, v80
	v_fmac_f32_e32 v30, v76, v86
	v_fmac_f32_e32 v25, v76, v87
	v_fmac_f32_e32 v24, v74, v87
	v_fmac_f32_e32 v23, v74, v88
	v_fmac_f32_e32 v26, v74, v78
	v_fmac_f32_e32 v21, v74, v89
	v_fmac_f32_e32 v20, v74, v79
	v_fmac_f32_e32 v22, v63, v78
	v_fmac_f32_e32 v17, v63, v89
	v_fmac_f32_e32 v16, v63, v79
	v_fmac_f32_e32 v18, v56, v89
	v_fmac_f32_e32 v14, v56, v79
	v_fmac_f32_e32 v13, v57, v79
	v_fmac_f32_e32 v30, v74, v112
	v_fmac_f32_e32 v25, v74, v86
	v_fmac_f32_e32 v24, v71, v86
	v_fmac_f32_e32 v23, v71, v87
	v_fmac_f32_e32 v26, v71, v88
	v_fmac_f32_e32 v21, v71, v78
	v_fmac_f32_e32 v20, v71, v89
	v_fmac_f32_e32 v19, v71, v79
	v_fmac_f32_e32 v22, v61, v88
	v_fmac_f32_e32 v17, v61, v78
	v_fmac_f32_e32 v16, v61, v89
	v_fmac_f32_e32 v15, v61, v79
	v_fmac_f32_e32 v18, v57, v78
	v_fmac_f32_e32 v14, v57, v89
	v_fmac_f32_e32 v13, v59, v89
	v_fmac_f32_e32 v30, v71, v84
	v_fmac_f32_e32 v25, v71, v112
	v_fmac_f32_e32 v24, v69, v112
	v_fmac_f32_e32 v23, v69, v86
	v_fmac_f32_e32 v26, v69, v87
	v_fmac_f32_e32 v21, v69, v88
	v_fmac_f32_e32 v20, v69, v78
	v_fmac_f32_e32 v19, v69, v89
	v_fmac_f32_e32 v22, v58, v87
	v_fmac_f32_e32 v17, v58, v88
	v_fmac_f32_e32 v16, v58, v78
	v_fmac_f32_e32 v15, v58, v89
	v_fmac_f32_e32 v18, v59, v88
	v_fmac_f32_e32 v14, v59, v78
	v_fmac_f32_e32 v13, v60, v78
; __device__ __forceinline__ void conv_tile(const Params& p, int l, int item, const bf16* PROJ, bf16* CV, LAS float* sl) {
;     ...
;     for (int t = 0; t < 32; ++t) { float acc = bias;
; #pragma unroll
;         for (int j = 0; j < 31; ++j) acc = fmaf(u[t + j], w[j], acc);
;         y[t] = acc; y2[t] = acc * acc; }
	v_fmac_f32_e32 v30, v69, v83
	v_fmac_f32_e32 v25, v69, v84
	v_fmac_f32_e32 v24, v66, v84
	v_fmac_f32_e32 v23, v66, v112
	v_fmac_f32_e32 v26, v66, v86
	v_fmac_f32_e32 v21, v66, v87
	v_fmac_f32_e32 v20, v66, v88
	v_fmac_f32_e32 v19, v66, v78
	v_fmac_f32_e32 v22, v56, v86
	v_fmac_f32_e32 v17, v56, v87
	v_fmac_f32_e32 v16, v56, v88
	v_fmac_f32_e32 v15, v56, v78
	v_fmac_f32_e32 v18, v60, v87
	v_fmac_f32_e32 v14, v60, v88
	v_fmac_f32_e32 v13, v62, v88
	v_fmac_f32_e32 v30, v66, v85
	v_fmac_f32_e32 v25, v66, v83
	v_fmac_f32_e32 v24, v63, v83
	v_fmac_f32_e32 v23, v63, v84
	v_fmac_f32_e32 v26, v63, v112
	v_fmac_f32_e32 v21, v63, v86
	v_fmac_f32_e32 v20, v63, v87
	v_fmac_f32_e32 v19, v63, v88
	v_fmac_f32_e32 v22, v57, v112
	v_fmac_f32_e32 v17, v57, v86
	v_fmac_f32_e32 v16, v57, v87
	v_fmac_f32_e32 v15, v57, v88
	v_fmac_f32_e32 v18, v62, v86
	v_fmac_f32_e32 v14, v62, v87
	v_fmac_f32_e32 v13, v64, v87
	v_fmac_f32_e32 v30, v63, v110
	v_fmac_f32_e32 v25, v63, v85
	v_fmac_f32_e32 v24, v61, v85
	v_fmac_f32_e32 v23, v61, v83
	v_fmac_f32_e32 v26, v61, v84
	v_fmac_f32_e32 v21, v61, v112
	v_fmac_f32_e32 v20, v61, v86
	v_fmac_f32_e32 v19, v61, v87
	v_fmac_f32_e32 v22, v59, v84
	v_fmac_f32_e32 v17, v59, v112
	v_fmac_f32_e32 v16, v59, v86
	v_fmac_f32_e32 v15, v59, v87
	v_fmac_f32_e32 v18, v64, v112
	v_fmac_f32_e32 v14, v64, v86
	v_fmac_f32_e32 v13, v65, v86
	v_fmac_f32_e32 v30, v61, v82
	v_fmac_f32_e32 v25, v61, v110
	v_fmac_f32_e32 v24, v58, v110
	v_fmac_f32_e32 v23, v58, v85
	v_fmac_f32_e32 v26, v58, v83
	v_fmac_f32_e32 v21, v58, v84
	v_fmac_f32_e32 v20, v58, v112
	v_fmac_f32_e32 v19, v58, v86
	v_fmac_f32_e32 v22, v60, v83
	v_fmac_f32_e32 v17, v60, v84
	v_fmac_f32_e32 v16, v60, v112
	v_fmac_f32_e32 v15, v60, v86
	v_fmac_f32_e32 v18, v65, v84
	v_fmac_f32_e32 v14, v65, v112
	v_fmac_f32_e32 v13, v67, v112
	v_fmac_f32_e32 v30, v58, v107
	v_fmac_f32_e32 v25, v58, v82
	v_fmac_f32_e32 v24, v56, v82
	v_fmac_f32_e32 v23, v56, v110
	v_fmac_f32_e32 v26, v56, v85
	v_fmac_f32_e32 v21, v56, v83
	v_fmac_f32_e32 v20, v56, v84
	v_fmac_f32_e32 v19, v56, v112
	v_fmac_f32_e32 v22, v62, v85
	v_fmac_f32_e32 v17, v62, v83
	v_fmac_f32_e32 v16, v62, v84
	v_fmac_f32_e32 v15, v62, v112
	v_fmac_f32_e32 v18, v67, v83
	v_fmac_f32_e32 v14, v67, v84
	v_fmac_f32_e32 v13, v68, v84
	v_fmac_f32_e32 v30, v56, v105
	v_fmac_f32_e32 v25, v56, v107
	v_fmac_f32_e32 v24, v57, v107
	v_fmac_f32_e32 v23, v57, v82
	v_fmac_f32_e32 v26, v57, v110
	v_fmac_f32_e32 v21, v57, v85
	v_fmac_f32_e32 v20, v57, v83
	v_fmac_f32_e32 v19, v57, v84
	v_fmac_f32_e32 v22, v64, v110
	v_fmac_f32_e32 v17, v64, v85
	v_fmac_f32_e32 v16, v64, v83
	v_fmac_f32_e32 v15, v64, v84
	v_fmac_f32_e32 v18, v68, v85
	v_fmac_f32_e32 v14, v68, v83
	v_fmac_f32_e32 v13, v70, v83
	v_fmac_f32_e32 v30, v57, v109
	v_fmac_f32_e32 v25, v57, v105
	v_fmac_f32_e32 v24, v59, v105
	v_fmac_f32_e32 v23, v59, v107
	v_fmac_f32_e32 v26, v59, v82
	v_fmac_f32_e32 v21, v59, v110
	v_fmac_f32_e32 v20, v59, v85
	v_fmac_f32_e32 v19, v59, v83
	v_fmac_f32_e32 v22, v65, v82
	v_fmac_f32_e32 v17, v65, v110
	v_fmac_f32_e32 v16, v65, v85
	v_fmac_f32_e32 v15, v65, v83
	v_fmac_f32_e32 v18, v70, v110
	v_fmac_f32_e32 v14, v70, v85
	v_fmac_f32_e32 v13, v72, v85
	v_fmac_f32_e32 v27, v111, v89
	v_fmac_f32_e32 v30, v59, v102
	v_fmac_f32_e32 v25, v59, v109
	v_fmac_f32_e32 v24, v60, v109
	v_fmac_f32_e32 v23, v60, v105
	v_fmac_f32_e32 v26, v60, v107
	v_fmac_f32_e32 v21, v60, v82
	v_fmac_f32_e32 v20, v60, v110
	v_fmac_f32_e32 v19, v60, v85
	v_fmac_f32_e32 v22, v67, v107
	v_fmac_f32_e32 v17, v67, v82
	v_fmac_f32_e32 v16, v67, v110
	v_fmac_f32_e32 v15, v67, v85
	v_fmac_f32_e32 v18, v72, v82
	v_fmac_f32_e32 v14, v72, v110
	v_fmac_f32_e32 v13, v73, v110
	v_fmac_f32_e32 v54, v111, v101
	v_fmac_f32_e32 v53, v111, v102
	v_fmac_f32_e32 v52, v111, v109
	v_fmac_f32_e32 v44, v111, v105
	v_fmac_f32_e32 v47, v111, v107
	v_fmac_f32_e32 v36, v111, v82
	v_fmac_f32_e32 v37, v111, v110
	v_fmac_f32_e32 v38, v111, v85
	v_fmac_f32_e32 v41, v111, v83
	v_fmac_f32_e32 v34, v111, v84
	v_fmac_f32_e32 v32, v111, v112
	v_fmac_f32_e32 v31, v111, v86
	v_fmac_f32_e32 v33, v111, v87
	v_fmac_f32_e32 v29, v111, v88
	v_fmac_f32_e32 v28, v111, v78
	v_fmac_f32_e32 v27, v91, v78
	v_fmac_f32_e32 v30, v60, v101
	v_fmac_f32_e32 v25, v60, v102
	v_fmac_f32_e32 v24, v62, v102
	v_fmac_f32_e32 v23, v62, v109
	v_fmac_f32_e32 v26, v62, v105
	v_fmac_f32_e32 v21, v62, v107
	v_fmac_f32_e32 v20, v62, v82
	v_fmac_f32_e32 v19, v62, v110
	v_fmac_f32_e32 v22, v68, v105
	v_fmac_f32_e32 v17, v68, v107
	v_fmac_f32_e32 v16, v68, v82
	v_fmac_f32_e32 v15, v68, v110
	v_fmac_f32_e32 v18, v73, v107
	v_fmac_f32_e32 v14, v73, v82
	v_fmac_f32_e32 v13, v75, v82
	v_fmac_f32_e32 v54, v91, v98
	v_fmac_f32_e32 v53, v91, v101
	v_fmac_f32_e32 v52, v91, v102
	v_fmac_f32_e32 v44, v91, v109
	v_fmac_f32_e32 v47, v91, v105
	v_fmac_f32_e32 v36, v91, v107
	v_fmac_f32_e32 v37, v91, v82
	v_fmac_f32_e32 v38, v91, v110
	v_fmac_f32_e32 v41, v91, v85
	v_fmac_f32_e32 v34, v91, v83
	v_fmac_f32_e32 v32, v91, v84
	v_fmac_f32_e32 v31, v91, v112
	v_fmac_f32_e32 v33, v91, v86
	v_fmac_f32_e32 v29, v91, v87
	v_fmac_f32_e32 v28, v91, v88
	v_fmac_f32_e32 v27, v90, v88
	v_fmac_f32_e32 v30, v62, v98
	v_fmac_f32_e32 v25, v62, v101
	v_fmac_f32_e32 v24, v64, v101
	v_fmac_f32_e32 v23, v64, v102
	v_fmac_f32_e32 v26, v64, v109
	v_fmac_f32_e32 v21, v64, v105
	v_fmac_f32_e32 v20, v64, v107
	v_fmac_f32_e32 v19, v64, v82
	v_fmac_f32_e32 v22, v70, v109
	v_fmac_f32_e32 v17, v70, v105
	v_fmac_f32_e32 v16, v70, v107
	v_fmac_f32_e32 v15, v70, v82
	v_fmac_f32_e32 v18, v75, v105
	v_fmac_f32_e32 v14, v75, v107
	v_fmac_f32_e32 v13, v115, v107
	s_waitcnt vmcnt(8)
; __device__ __forceinline__ void conv_tile(const Params& p, int l, int item, const bf16* PROJ, bf16* CV, LAS float* sl) {
;     ...
;     for (int t = 0; t < 32; ++t) { float acc = bias;
; #pragma unroll
;         for (int j = 0; j < 31; ++j) acc = fmaf(u[t + j], w[j], acc);
;         y[t] = acc; y2[t] = acc * acc; }
	v_fmac_f32_e32 v54, v90, v108
	v_fmac_f32_e32 v53, v90, v98
	v_fmac_f32_e32 v52, v90, v101
	v_fmac_f32_e32 v44, v90, v102
	v_fmac_f32_e32 v47, v90, v109
	v_fmac_f32_e32 v36, v90, v105
	v_fmac_f32_e32 v37, v90, v107
	v_fmac_f32_e32 v38, v90, v82
	v_fmac_f32_e32 v41, v90, v110
	v_fmac_f32_e32 v34, v90, v85
	v_fmac_f32_e32 v32, v90, v83
	v_fmac_f32_e32 v31, v90, v84
	v_fmac_f32_e32 v33, v90, v112
	v_fmac_f32_e32 v29, v90, v86
	v_fmac_f32_e32 v28, v90, v87
	v_fmac_f32_e32 v27, v81, v87
	v_fmac_f32_e32 v30, v64, v108
	v_fmac_f32_e32 v25, v64, v98
	v_fmac_f32_e32 v24, v65, v98
	v_fmac_f32_e32 v23, v65, v101
	v_fmac_f32_e32 v26, v65, v102
	v_fmac_f32_e32 v21, v65, v109
	v_fmac_f32_e32 v20, v65, v105
	v_fmac_f32_e32 v19, v65, v107
	v_fmac_f32_e32 v22, v72, v102
	v_fmac_f32_e32 v17, v72, v109
	v_fmac_f32_e32 v16, v72, v105
	v_fmac_f32_e32 v15, v72, v107
	v_fmac_f32_e32 v18, v115, v109
	v_fmac_f32_e32 v14, v115, v105
	v_fmac_f32_e32 v13, v116, v105
	v_fmac_f32_e32 v54, v81, v94
	v_fmac_f32_e32 v53, v81, v108
	v_fmac_f32_e32 v52, v81, v98
	v_fmac_f32_e32 v44, v81, v101
	v_fmac_f32_e32 v47, v81, v102
	v_fmac_f32_e32 v36, v81, v109
	v_fmac_f32_e32 v37, v81, v105
	v_fmac_f32_e32 v38, v81, v107
	v_fmac_f32_e32 v41, v81, v82
	v_fmac_f32_e32 v34, v81, v110
	v_fmac_f32_e32 v32, v81, v85
	v_fmac_f32_e32 v31, v81, v83
	v_fmac_f32_e32 v33, v81, v84
	v_fmac_f32_e32 v29, v81, v112
	v_fmac_f32_e32 v28, v81, v86
	v_fmac_f32_e32 v27, v77, v86
	v_fmac_f32_e32 v30, v65, v94
	v_fmac_f32_e32 v25, v65, v108
	v_fmac_f32_e32 v24, v67, v108
	v_fmac_f32_e32 v23, v67, v98
	v_fmac_f32_e32 v26, v67, v101
	v_fmac_f32_e32 v21, v67, v102
	v_fmac_f32_e32 v20, v67, v109
	v_fmac_f32_e32 v19, v67, v105
	v_fmac_f32_e32 v22, v73, v101
	v_fmac_f32_e32 v17, v73, v102
	v_fmac_f32_e32 v16, v73, v109
	v_fmac_f32_e32 v15, v73, v105
	v_fmac_f32_e32 v18, v116, v102
	v_fmac_f32_e32 v14, v116, v109
	v_fmac_f32_e32 v13, v117, v109
	v_fmac_f32_e32 v54, v77, v93
	v_fmac_f32_e32 v53, v77, v94
	v_fmac_f32_e32 v52, v77, v108
	v_fmac_f32_e32 v44, v77, v98
	v_fmac_f32_e32 v47, v77, v101
	v_fmac_f32_e32 v36, v77, v102
	v_fmac_f32_e32 v37, v77, v109
	v_fmac_f32_e32 v38, v77, v105
	v_fmac_f32_e32 v41, v77, v107
	v_fmac_f32_e32 v34, v77, v82
	v_fmac_f32_e32 v32, v77, v110
	v_fmac_f32_e32 v31, v77, v85
	v_fmac_f32_e32 v33, v77, v83
	v_fmac_f32_e32 v29, v77, v84
	v_fmac_f32_e32 v28, v77, v112
	v_fmac_f32_e32 v27, v76, v112
	v_fmac_f32_e32 v30, v67, v93
	v_fmac_f32_e32 v25, v67, v94
	v_fmac_f32_e32 v24, v68, v94
	v_fmac_f32_e32 v23, v68, v108
	v_fmac_f32_e32 v26, v68, v98
	v_fmac_f32_e32 v21, v68, v101
	v_fmac_f32_e32 v20, v68, v102
	v_fmac_f32_e32 v19, v68, v109
	v_fmac_f32_e32 v22, v75, v98
	v_fmac_f32_e32 v17, v75, v101
	v_fmac_f32_e32 v16, v75, v102
	v_fmac_f32_e32 v15, v75, v109
	v_fmac_f32_e32 v18, v117, v101
	v_fmac_f32_e32 v14, v117, v102
	v_fmac_f32_e32 v13, v6, v102
	v_fmac_f32_e32 v54, v76, v92
	v_fmac_f32_e32 v53, v76, v93
	v_fmac_f32_e32 v52, v76, v94
	v_fmac_f32_e32 v44, v76, v108
	v_fmac_f32_e32 v47, v76, v98
	v_fmac_f32_e32 v36, v76, v101
	v_fmac_f32_e32 v37, v76, v102
	v_fmac_f32_e32 v38, v76, v109
	v_fmac_f32_e32 v41, v76, v105
	v_fmac_f32_e32 v34, v76, v107
	v_fmac_f32_e32 v32, v76, v82
	v_fmac_f32_e32 v31, v76, v110
	v_fmac_f32_e32 v33, v76, v85
	v_fmac_f32_e32 v29, v76, v83
	v_fmac_f32_e32 v28, v76, v84
	v_fmac_f32_e32 v27, v74, v84
	v_fmac_f32_e32 v30, v68, v92
	v_fmac_f32_e32 v25, v68, v93
	v_fmac_f32_e32 v24, v70, v93
	v_fmac_f32_e32 v23, v70, v94
	v_fmac_f32_e32 v26, v70, v108
	v_fmac_f32_e32 v21, v70, v98
	v_fmac_f32_e32 v20, v70, v101
	v_fmac_f32_e32 v19, v70, v102
	v_fmac_f32_e32 v22, v115, v108
	v_fmac_f32_e32 v17, v115, v98
	v_fmac_f32_e32 v16, v115, v101
	v_fmac_f32_e32 v15, v115, v102
	v_fmac_f32_e32 v18, v6, v98
	v_fmac_f32_e32 v14, v6, v101
	v_fmac_f32_e32 v13, v8, v101
	s_waitcnt vmcnt(7)
	v_fmac_f32_e32 v54, v74, v96
	v_fmac_f32_e32 v53, v74, v92
	v_fmac_f32_e32 v52, v74, v93
	v_fmac_f32_e32 v44, v74, v94
	v_fmac_f32_e32 v47, v74, v108
	v_fmac_f32_e32 v36, v74, v98
	v_fmac_f32_e32 v37, v74, v101
	v_fmac_f32_e32 v38, v74, v102
	v_fmac_f32_e32 v41, v74, v109
	v_fmac_f32_e32 v34, v74, v105
	v_fmac_f32_e32 v32, v74, v107
	v_fmac_f32_e32 v31, v74, v82
	v_fmac_f32_e32 v33, v74, v110
	v_fmac_f32_e32 v29, v74, v85
	v_fmac_f32_e32 v28, v74, v83
	v_fmac_f32_e32 v27, v71, v83
	v_fmac_f32_e32 v30, v70, v96
	v_fmac_f32_e32 v25, v70, v92
	v_fmac_f32_e32 v24, v72, v92
	v_fmac_f32_e32 v23, v72, v93
	v_fmac_f32_e32 v26, v72, v94
	v_fmac_f32_e32 v21, v72, v108
	v_fmac_f32_e32 v20, v72, v98
	v_fmac_f32_e32 v19, v72, v101
	v_fmac_f32_e32 v22, v116, v94
	v_fmac_f32_e32 v17, v116, v108
	v_fmac_f32_e32 v16, v116, v98
	v_fmac_f32_e32 v15, v116, v101
	v_fmac_f32_e32 v18, v8, v108
	v_fmac_f32_e32 v14, v8, v98
	v_fmac_f32_e32 v13, v7, v98
	s_waitcnt vmcnt(5)
	v_fmac_f32_e32 v54, v71, v106
	v_fmac_f32_e32 v53, v71, v96
	v_fmac_f32_e32 v52, v71, v92
	v_fmac_f32_e32 v44, v71, v93
	v_fmac_f32_e32 v47, v71, v94
	v_fmac_f32_e32 v36, v71, v108
	v_fmac_f32_e32 v37, v71, v98
	v_fmac_f32_e32 v38, v71, v101
	v_fmac_f32_e32 v41, v71, v102
	v_fmac_f32_e32 v34, v71, v109
	v_fmac_f32_e32 v32, v71, v105
	v_fmac_f32_e32 v31, v71, v107
	v_fmac_f32_e32 v33, v71, v82
	v_fmac_f32_e32 v29, v71, v110
	v_fmac_f32_e32 v28, v71, v85
	v_fmac_f32_e32 v27, v69, v85
	v_fmac_f32_e32 v30, v72, v106
	v_fmac_f32_e32 v25, v72, v96
	v_fmac_f32_e32 v24, v73, v96
	v_fmac_f32_e32 v23, v73, v92
	v_fmac_f32_e32 v26, v73, v93
	v_fmac_f32_e32 v21, v73, v94
	v_fmac_f32_e32 v20, v73, v108
	v_fmac_f32_e32 v19, v73, v98
	v_fmac_f32_e32 v22, v117, v93
	v_fmac_f32_e32 v17, v117, v94
	v_fmac_f32_e32 v16, v117, v108
	v_fmac_f32_e32 v15, v117, v98
	v_fmac_f32_e32 v18, v7, v94
	v_fmac_f32_e32 v14, v7, v108
	v_fmac_f32_e32 v13, v35, v108
	v_fmac_f32_e32 v55, v111, v98
	s_waitcnt vmcnt(4)
; __device__ __forceinline__ void conv_tile(const Params& p, int l, int item, const bf16* PROJ, bf16* CV, LAS float* sl) {
;     ...
;     for (int t = 0; t < 32; ++t) { float acc = bias;
; #pragma unroll
;         for (int j = 0; j < 31; ++j) acc = fmaf(u[t + j], w[j], acc);
;         y[t] = acc; y2[t] = acc * acc; }
	v_fmac_f32_e32 v54, v69, v104
	v_fmac_f32_e32 v53, v69, v106
	v_fmac_f32_e32 v52, v69, v96
	v_fmac_f32_e32 v44, v69, v92
	v_fmac_f32_e32 v47, v69, v93
	v_fmac_f32_e32 v36, v69, v94
	v_fmac_f32_e32 v37, v69, v108
	v_fmac_f32_e32 v38, v69, v98
	v_fmac_f32_e32 v41, v69, v101
	v_fmac_f32_e32 v34, v69, v102
	v_fmac_f32_e32 v32, v69, v109
	v_fmac_f32_e32 v31, v69, v105
	v_fmac_f32_e32 v33, v69, v107
	v_fmac_f32_e32 v29, v69, v82
	v_fmac_f32_e32 v28, v69, v110
	v_fmac_f32_e32 v27, v66, v110
	v_fmac_f32_e32 v30, v73, v104
	v_fmac_f32_e32 v25, v73, v106
	v_fmac_f32_e32 v24, v75, v106
	v_fmac_f32_e32 v23, v75, v96
	v_fmac_f32_e32 v26, v75, v92
	v_fmac_f32_e32 v21, v75, v93
	v_fmac_f32_e32 v20, v75, v94
	v_fmac_f32_e32 v19, v75, v108
	v_fmac_f32_e32 v22, v6, v92
	v_fmac_f32_e32 v17, v6, v93
	v_fmac_f32_e32 v16, v6, v94
	v_fmac_f32_e32 v15, v6, v108
	v_fmac_f32_e32 v18, v35, v93
	v_fmac_f32_e32 v14, v35, v94
	v_fmac_f32_e32 v13, v9, v94
	v_fmac_f32_e32 v55, v91, v108
	s_waitcnt vmcnt(3)
	v_fmac_f32_e32 v54, v66, v103
	v_fmac_f32_e32 v53, v66, v104
	v_fmac_f32_e32 v52, v66, v106
	v_fmac_f32_e32 v44, v66, v96
	v_fmac_f32_e32 v47, v66, v92
	v_fmac_f32_e32 v36, v66, v93
	v_fmac_f32_e32 v37, v66, v94
	v_fmac_f32_e32 v38, v66, v108
	v_fmac_f32_e32 v41, v66, v98
	v_fmac_f32_e32 v34, v66, v101
	v_fmac_f32_e32 v32, v66, v102
	v_fmac_f32_e32 v31, v66, v109
	v_fmac_f32_e32 v33, v66, v105
	v_fmac_f32_e32 v29, v66, v107
	v_fmac_f32_e32 v28, v66, v82
	v_fmac_f32_e32 v27, v63, v82
	v_fmac_f32_e32 v30, v75, v103
	v_fmac_f32_e32 v25, v75, v104
	v_fmac_f32_e32 v24, v115, v104
	v_fmac_f32_e32 v23, v115, v106
	v_fmac_f32_e32 v26, v115, v96
	v_fmac_f32_e32 v21, v115, v92
	v_fmac_f32_e32 v20, v115, v93
	v_fmac_f32_e32 v19, v115, v94
	v_fmac_f32_e32 v22, v8, v96
	v_fmac_f32_e32 v17, v8, v92
	v_fmac_f32_e32 v16, v8, v93
	v_fmac_f32_e32 v15, v8, v94
	v_fmac_f32_e32 v18, v9, v92
	v_fmac_f32_e32 v14, v9, v93
	v_fmac_f32_e32 v13, v40, v93
	v_fmac_f32_e32 v55, v90, v94
	v_fmac_f32_e32 v54, v63, v95
	v_fmac_f32_e32 v53, v63, v103
	v_fmac_f32_e32 v52, v63, v104
	v_fmac_f32_e32 v44, v63, v106
	v_fmac_f32_e32 v47, v63, v96
	v_fmac_f32_e32 v36, v63, v92
	v_fmac_f32_e32 v37, v63, v93
	v_fmac_f32_e32 v38, v63, v94
	v_fmac_f32_e32 v41, v63, v108
	v_fmac_f32_e32 v34, v63, v98
	v_fmac_f32_e32 v32, v63, v101
	v_fmac_f32_e32 v31, v63, v102
	v_fmac_f32_e32 v33, v63, v109
	v_fmac_f32_e32 v29, v63, v105
	v_fmac_f32_e32 v28, v63, v107
	v_fmac_f32_e32 v27, v61, v107
	v_fmac_f32_e32 v30, v115, v95
	v_fmac_f32_e32 v25, v115, v103
	v_fmac_f32_e32 v24, v116, v103
	v_fmac_f32_e32 v23, v116, v104
	v_fmac_f32_e32 v26, v116, v106
	v_fmac_f32_e32 v21, v116, v96
	v_fmac_f32_e32 v20, v116, v92
	v_fmac_f32_e32 v19, v116, v93
	v_fmac_f32_e32 v22, v7, v106
	v_fmac_f32_e32 v17, v7, v96
	v_fmac_f32_e32 v16, v7, v92
	v_fmac_f32_e32 v15, v7, v93
	v_fmac_f32_e32 v18, v40, v96
	v_fmac_f32_e32 v14, v40, v92
	v_fmac_f32_e32 v13, v39, v92
	v_fmac_f32_e32 v55, v81, v93
	s_waitcnt vmcnt(2)
	v_fmac_f32_e32 v54, v61, v99
	v_fmac_f32_e32 v53, v61, v95
	v_fmac_f32_e32 v52, v61, v103
	v_fmac_f32_e32 v44, v61, v104
	v_fmac_f32_e32 v47, v61, v106
	v_fmac_f32_e32 v36, v61, v96
	v_fmac_f32_e32 v37, v61, v92
	v_fmac_f32_e32 v38, v61, v93
	v_fmac_f32_e32 v41, v61, v94
	v_fmac_f32_e32 v34, v61, v108
	v_fmac_f32_e32 v32, v61, v98
	v_fmac_f32_e32 v31, v61, v101
	v_fmac_f32_e32 v33, v61, v102
	v_fmac_f32_e32 v29, v61, v109
	v_fmac_f32_e32 v28, v61, v105
	v_fmac_f32_e32 v27, v58, v105
	v_fmac_f32_e32 v30, v116, v99
	v_fmac_f32_e32 v25, v116, v95
	v_fmac_f32_e32 v24, v117, v95
	v_fmac_f32_e32 v23, v117, v103
	v_fmac_f32_e32 v26, v117, v104
	v_fmac_f32_e32 v21, v117, v106
	v_fmac_f32_e32 v20, v117, v96
	v_fmac_f32_e32 v19, v117, v92
	v_fmac_f32_e32 v22, v35, v104
	v_fmac_f32_e32 v17, v35, v106
	v_fmac_f32_e32 v16, v35, v96
	v_fmac_f32_e32 v15, v35, v92
	v_fmac_f32_e32 v18, v39, v106
	v_fmac_f32_e32 v14, v39, v96
	v_fmac_f32_e32 v13, v43, v96
	v_fmac_f32_e32 v55, v77, v92
	s_waitcnt vmcnt(1)
	v_fmac_f32_e32 v54, v58, v97
	v_fmac_f32_e32 v53, v58, v99
	v_fmac_f32_e32 v52, v58, v95
	v_fmac_f32_e32 v44, v58, v103
	v_fmac_f32_e32 v47, v58, v104
	v_fmac_f32_e32 v36, v58, v106
	v_fmac_f32_e32 v37, v58, v96
	v_fmac_f32_e32 v38, v58, v92
	v_fmac_f32_e32 v41, v58, v93
	v_fmac_f32_e32 v34, v58, v94
	v_fmac_f32_e32 v32, v58, v108
	v_fmac_f32_e32 v31, v58, v98
	v_fmac_f32_e32 v33, v58, v101
	v_fmac_f32_e32 v29, v58, v102
	v_fmac_f32_e32 v28, v58, v109
	v_fmac_f32_e32 v27, v56, v109
	v_fmac_f32_e32 v30, v117, v97
	v_fmac_f32_e32 v25, v117, v99
	v_fmac_f32_e32 v24, v6, v99
	v_fmac_f32_e32 v23, v6, v95
	v_fmac_f32_e32 v26, v6, v103
	v_fmac_f32_e32 v21, v6, v104
	v_fmac_f32_e32 v20, v6, v106
	v_fmac_f32_e32 v19, v6, v96
	v_fmac_f32_e32 v22, v9, v103
	v_fmac_f32_e32 v17, v9, v104
	v_fmac_f32_e32 v16, v9, v106
	v_fmac_f32_e32 v15, v9, v96
	v_fmac_f32_e32 v18, v43, v104
	v_fmac_f32_e32 v14, v43, v106
	v_fmac_f32_e32 v13, v42, v106
	v_fmac_f32_e32 v55, v76, v96
	s_waitcnt vmcnt(0)
; __device__ __forceinline__ float wave_reduce32(const float (&v)[32], int lane) {
;     float a[16], b[8], c[4], d[2], e;
;     { const bool h = lane & 32;
; #pragma unroll
;       for (int t = 0; t < 16; ++t) { const float keep = h ? v[t + 16] : v[t], send = h ? v[t] : v[t + 16]; a[t] = keep + __shfl_xor(send, 32); } }
; __device__ __forceinline__ void conv_tile(const Params& p, int l, int item, const bf16* PROJ, bf16* CV, LAS float* sl) {
;     ...
;     for (int t = 0; t < 32; ++t) { float acc = bias;
; #pragma unroll
;         for (int j = 0; j < 31; ++j) acc = fmaf(u[t + j], w[j], acc);
;         y[t] = acc; y2[t] = acc * acc; }
;     const float r1 = wave_reduce32(y, lane), r2 = wave_reduce32(y2, lane);
	v_fmac_f32_e32 v54, v56, v100
	v_fmac_f32_e32 v53, v56, v97
	v_fmac_f32_e32 v52, v56, v99
	v_fmac_f32_e32 v44, v56, v95
	v_fmac_f32_e32 v47, v56, v103
	v_fmac_f32_e32 v36, v56, v104
	v_fmac_f32_e32 v37, v56, v106
	v_fmac_f32_e32 v38, v56, v96
	v_fmac_f32_e32 v41, v56, v92
	v_fmac_f32_e32 v34, v56, v93
	v_fmac_f32_e32 v32, v56, v94
	v_fmac_f32_e32 v31, v56, v108
	v_fmac_f32_e32 v33, v56, v98
	v_fmac_f32_e32 v29, v56, v101
	v_fmac_f32_e32 v28, v56, v102
	v_fmac_f32_e32 v27, v57, v102
	v_fmac_f32_e32 v30, v6, v100
	v_fmac_f32_e32 v25, v6, v97
	v_fmac_f32_e32 v24, v8, v97
	v_fmac_f32_e32 v23, v8, v99
	v_fmac_f32_e32 v26, v8, v95
	v_fmac_f32_e32 v21, v8, v103
	v_fmac_f32_e32 v20, v8, v104
	v_fmac_f32_e32 v19, v8, v106
	v_fmac_f32_e32 v22, v40, v95
	v_fmac_f32_e32 v17, v40, v103
	v_fmac_f32_e32 v16, v40, v104
	v_fmac_f32_e32 v15, v40, v106
	v_fmac_f32_e32 v18, v42, v103
	v_fmac_f32_e32 v14, v42, v104
	v_fmac_f32_e32 v13, v46, v104
	v_cmp_eq_u32_e64 s[0:1], 0, v114
	v_fmac_f32_e32 v55, v74, v106
	v_fmac_f32_e32 v53, v57, v100
	v_fmac_f32_e32 v52, v57, v97
	v_fmac_f32_e32 v44, v57, v99
	v_fmac_f32_e32 v47, v57, v95
	v_fmac_f32_e32 v36, v57, v103
	v_fmac_f32_e32 v37, v57, v104
	v_fmac_f32_e32 v38, v57, v106
	v_fmac_f32_e32 v41, v57, v96
	v_fmac_f32_e32 v34, v57, v92
	v_fmac_f32_e32 v32, v57, v93
	v_fmac_f32_e32 v31, v57, v94
	v_fmac_f32_e32 v33, v57, v108
	v_fmac_f32_e32 v29, v57, v98
	v_fmac_f32_e32 v28, v57, v101
	v_fmac_f32_e32 v27, v59, v101
	v_fmac_f32_e32 v25, v8, v100
	v_fmac_f32_e32 v24, v7, v100
	v_fmac_f32_e32 v23, v7, v97
	v_fmac_f32_e32 v26, v7, v99
	v_fmac_f32_e32 v21, v7, v95
	v_fmac_f32_e32 v20, v7, v103
	v_fmac_f32_e32 v19, v7, v104
	v_fmac_f32_e32 v22, v39, v99
	v_fmac_f32_e32 v17, v39, v95
	v_fmac_f32_e32 v16, v39, v103
	v_fmac_f32_e32 v15, v39, v104
	v_fmac_f32_e32 v18, v46, v95
	v_fmac_f32_e32 v14, v46, v103
	v_fmac_f32_e32 v13, v45, v103
	v_cndmask_b32_e64 v7, v54, v30, s[0:1]
	v_fmac_f32_e32 v55, v71, v104
	v_fmac_f32_e32 v52, v59, v100
	v_fmac_f32_e32 v44, v59, v97
	v_fmac_f32_e32 v47, v59, v99
	v_fmac_f32_e32 v36, v59, v95
	v_fmac_f32_e32 v37, v59, v103
	v_fmac_f32_e32 v38, v59, v104
	v_fmac_f32_e32 v41, v59, v106
	v_fmac_f32_e32 v34, v59, v96
	v_fmac_f32_e32 v32, v59, v92
	v_fmac_f32_e32 v31, v59, v93
	v_fmac_f32_e32 v33, v59, v94
	v_fmac_f32_e32 v29, v59, v108
	v_fmac_f32_e32 v28, v59, v98
	v_fmac_f32_e32 v27, v60, v98
	v_fmac_f32_e32 v22, v43, v97
	v_fmac_f32_e32 v17, v43, v99
	v_fmac_f32_e32 v16, v43, v95
	v_fmac_f32_e32 v15, v43, v103
	v_fmac_f32_e32 v18, v45, v99
	v_fmac_f32_e32 v14, v45, v95
	v_fmac_f32_e32 v13, v49, v95
	ds_bpermute_b32 v8, v186, v7
	v_cndmask_b32_e64 v7, v53, v25, s[0:1]
	v_fmac_f32_e32 v55, v69, v103
	v_fmac_f32_e32 v44, v60, v100
	v_fmac_f32_e32 v47, v60, v97
	v_fmac_f32_e32 v36, v60, v99
	v_fmac_f32_e32 v37, v60, v95
	v_fmac_f32_e32 v38, v60, v103
	v_fmac_f32_e32 v41, v60, v104
	v_fmac_f32_e32 v34, v60, v106
	v_fmac_f32_e32 v32, v60, v96
	v_fmac_f32_e32 v31, v60, v92
	v_fmac_f32_e32 v33, v60, v93
	v_fmac_f32_e32 v29, v60, v94
	v_fmac_f32_e32 v28, v60, v108
	v_fmac_f32_e32 v27, v62, v108
	v_fmac_f32_e32 v23, v35, v100
	v_fmac_f32_e32 v26, v35, v97
	v_fmac_f32_e32 v21, v35, v99
	v_fmac_f32_e32 v20, v35, v95
	v_fmac_f32_e32 v19, v35, v103
	v_fmac_f32_e32 v22, v42, v100
	v_fmac_f32_e32 v17, v42, v97
	v_fmac_f32_e32 v16, v42, v99
	v_fmac_f32_e32 v15, v42, v95
	v_fmac_f32_e32 v18, v49, v97
	v_fmac_f32_e32 v14, v49, v99
	v_fmac_f32_e32 v13, v48, v99
	ds_bpermute_b32 v42, v186, v7
	v_cndmask_b32_e64 v7, v52, v24, s[0:1]
	v_fmac_f32_e32 v55, v66, v95
	v_fmac_f32_e32 v47, v62, v100
	v_fmac_f32_e32 v36, v62, v97
	v_fmac_f32_e32 v37, v62, v99
	v_fmac_f32_e32 v38, v62, v95
	v_fmac_f32_e32 v41, v62, v103
	v_fmac_f32_e32 v34, v62, v104
	v_fmac_f32_e32 v32, v62, v106
	v_fmac_f32_e32 v31, v62, v96
	v_fmac_f32_e32 v33, v62, v92
	v_fmac_f32_e32 v29, v62, v93
	v_fmac_f32_e32 v28, v62, v94
	v_fmac_f32_e32 v27, v64, v94
	v_fmac_f32_e32 v26, v9, v100
	v_fmac_f32_e32 v21, v9, v97
	v_fmac_f32_e32 v20, v9, v99
	v_fmac_f32_e32 v19, v9, v95
	v_fmac_f32_e32 v18, v48, v100
	v_fmac_f32_e32 v14, v48, v97
	v_fmac_f32_e32 v13, v51, v97
	ds_bpermute_b32 v48, v186, v7
	v_cndmask_b32_e64 v7, v44, v23, s[0:1]
	v_fmac_f32_e32 v55, v63, v99
	v_fmac_f32_e32 v36, v64, v100
	v_fmac_f32_e32 v37, v64, v97
	v_fmac_f32_e32 v38, v64, v99
	v_fmac_f32_e32 v41, v64, v95
	v_fmac_f32_e32 v34, v64, v103
	v_fmac_f32_e32 v32, v64, v104
	v_fmac_f32_e32 v31, v64, v106
	v_fmac_f32_e32 v33, v64, v96
	v_fmac_f32_e32 v29, v64, v92
	v_fmac_f32_e32 v28, v64, v93
	v_fmac_f32_e32 v27, v65, v93
	v_fmac_f32_e32 v21, v40, v100
	v_fmac_f32_e32 v20, v40, v97
	v_fmac_f32_e32 v19, v40, v99
	v_fmac_f32_e32 v13, v50, v100
	ds_bpermute_b32 v50, v186, v7
	v_cndmask_b32_e64 v7, v47, v26, s[0:1]
	v_fmac_f32_e32 v55, v61, v97
	v_fmac_f32_e32 v37, v65, v100
	v_fmac_f32_e32 v38, v65, v97
	v_fmac_f32_e32 v41, v65, v99
	v_fmac_f32_e32 v34, v65, v95
	v_fmac_f32_e32 v32, v65, v103
	v_fmac_f32_e32 v31, v65, v104
	v_fmac_f32_e32 v33, v65, v106
	v_fmac_f32_e32 v29, v65, v96
	v_fmac_f32_e32 v28, v65, v92
	v_fmac_f32_e32 v27, v67, v92
	v_fmac_f32_e32 v20, v39, v100
	v_fmac_f32_e32 v19, v39, v97
	ds_bpermute_b32 v56, v186, v7
	v_cndmask_b32_e64 v7, v36, v21, s[0:1]
	v_fmac_f32_e32 v55, v58, v100
	v_fmac_f32_e32 v38, v67, v100
	v_fmac_f32_e32 v41, v67, v97
	v_fmac_f32_e32 v34, v67, v99
	v_fmac_f32_e32 v32, v67, v95
	v_fmac_f32_e32 v31, v67, v103
	v_fmac_f32_e32 v33, v67, v104
	v_fmac_f32_e32 v29, v67, v106
	v_fmac_f32_e32 v28, v67, v96
	v_fmac_f32_e32 v27, v68, v96
	v_fmac_f32_e32 v19, v43, v100
	ds_bpermute_b32 v58, v186, v7
	v_cndmask_b32_e64 v7, v37, v20, s[0:1]
	v_fmac_f32_e32 v41, v68, v100
; __device__ __forceinline__ float wave_reduce32(const float (&v)[32], int lane) {
;     float a[16], b[8], c[4], d[2], e;
;     { const bool h = lane & 32;
; #pragma unroll
;       for (int t = 0; t < 16; ++t) { const float keep = h ? v[t + 16] : v[t], send = h ? v[t] : v[t + 16]; a[t] = keep + __shfl_xor(send, 32); } }
;     { const bool h = lane & 16;
; #pragma unroll
;       for (int t = 0; t < 8; ++t) { const float keep = h ? a[t + 8] : a[t], send = h ? a[t] : a[t + 8]; b[t] = keep + __shfl_xor(send, 16); } }
;     { const bool h = lane & 8;
; #pragma unroll
;       for (int t = 0; t < 4; ++t) { const float keep = h ? b[t + 4] : b[t], send = h ? b[t] : b[t + 4]; c[t] = keep + __shfl_xor(send, 8); } }
; __device__ __forceinline__ void conv_tile(const Params& p, int l, int item, const bf16* PROJ, bf16* CV, LAS float* sl) {
;     ...
;         y[t] = acc; y2[t] = acc * acc; }
;     const float r1 = wave_reduce32(y, lane), r2 = wave_reduce32(y2, lane);
	v_fmac_f32_e32 v34, v68, v97
	v_fmac_f32_e32 v32, v68, v99
	v_fmac_f32_e32 v31, v68, v95
	v_fmac_f32_e32 v33, v68, v103
	v_fmac_f32_e32 v29, v68, v104
	v_fmac_f32_e32 v28, v68, v106
	v_fmac_f32_e32 v27, v70, v106
	ds_bpermute_b32 v60, v186, v7
	v_cndmask_b32_e64 v7, v38, v19, s[0:1]
	v_fmac_f32_e32 v34, v70, v100
	v_fmac_f32_e32 v32, v70, v97
	v_fmac_f32_e32 v31, v70, v99
	v_fmac_f32_e32 v33, v70, v95
	v_fmac_f32_e32 v29, v70, v103
	v_fmac_f32_e32 v28, v70, v104
	v_fmac_f32_e32 v27, v72, v104
	v_fmac_f32_e32 v17, v46, v100
	v_fmac_f32_e32 v16, v46, v97
	v_fmac_f32_e32 v15, v46, v99
	ds_bpermute_b32 v62, v186, v7
	v_cndmask_b32_e64 v7, v41, v22, s[0:1]
	v_fmac_f32_e32 v32, v72, v100
	v_fmac_f32_e32 v31, v72, v97
	v_fmac_f32_e32 v33, v72, v99
	v_fmac_f32_e32 v29, v72, v95
	v_fmac_f32_e32 v28, v72, v103
	v_fmac_f32_e32 v27, v73, v103
	v_fmac_f32_e32 v16, v45, v100
	v_fmac_f32_e32 v15, v45, v97
	ds_bpermute_b32 v64, v186, v7
	v_cndmask_b32_e64 v7, v34, v17, s[0:1]
	v_fmac_f32_e32 v31, v73, v100
	v_fmac_f32_e32 v33, v73, v97
	v_fmac_f32_e32 v29, v73, v99
	v_fmac_f32_e32 v28, v73, v95
	v_fmac_f32_e32 v27, v75, v95
	v_fmac_f32_e32 v15, v49, v100
	ds_bpermute_b32 v66, v186, v7
	v_cndmask_b32_e64 v7, v32, v16, s[0:1]
	v_fmac_f32_e32 v33, v75, v100
	v_fmac_f32_e32 v29, v75, v97
	v_fmac_f32_e32 v28, v75, v99
	v_fmac_f32_e32 v27, v115, v99
	ds_bpermute_b32 v68, v186, v7
	v_cndmask_b32_e64 v7, v31, v15, s[0:1]
	v_fmac_f32_e32 v29, v115, v100
	v_fmac_f32_e32 v28, v115, v97
	v_fmac_f32_e32 v27, v116, v97
	v_fmac_f32_e32 v14, v51, v100
	ds_bpermute_b32 v70, v186, v7
	v_cndmask_b32_e64 v7, v33, v18, s[0:1]
	v_fmac_f32_e32 v28, v116, v100
	v_fmac_f32_e32 v27, v117, v100
	ds_bpermute_b32 v72, v186, v7
	v_cndmask_b32_e64 v7, v29, v14, s[0:1]
	v_mul_f32_e32 v113, v55, v55
	v_mul_f32_e32 v119, v27, v27
	ds_bpermute_b32 v78, v186, v7
	v_cndmask_b32_e64 v7, v28, v13, s[0:1]
	v_mul_f32_e32 v127, v38, v38
	v_mul_f32_e32 v74, v19, v19
	v_cndmask_b32_e64 v6, v55, v27, s[0:1]
	ds_bpermute_b32 v82, v186, v7
	v_cndmask_b32_e64 v7, v113, v119, s[0:1]
	v_mul_f32_e32 v118, v54, v54
	v_mul_f32_e32 v134, v30, v30
	ds_bpermute_b32 v6, v186, v6
	ds_bpermute_b32 v7, v186, v7
	v_cndmask_b32_e64 v63, v127, v74, s[0:1]
	v_mul_f32_e32 v128, v41, v41
	v_mul_f32_e32 v135, v22, v22
	v_cndmask_b32_e64 v9, v118, v134, s[0:1]
	ds_bpermute_b32 v63, v186, v63
	v_mul_f32_e32 v120, v53, v53
	v_mul_f32_e32 v133, v29, v29
	v_mul_f32_e32 v111, v25, v25
	v_mul_f32_e32 v140, v14, v14
	ds_bpermute_b32 v9, v186, v9
	v_cndmask_b32_e64 v65, v128, v135, s[0:1]
	v_mul_f32_e32 v122, v52, v52
	v_mul_f32_e32 v126, v37, v37
	v_mul_f32_e32 v129, v34, v34
	v_mul_f32_e32 v121, v28, v28
	v_mul_f32_e32 v91, v24, v24
	v_mul_f32_e32 v76, v20, v20
	v_mul_f32_e32 v136, v17, v17
	v_mul_f32_e32 v35, v13, v13
	v_cndmask_b32_e64 v43, v120, v111, s[0:1]
	ds_bpermute_b32 v65, v186, v65
	v_cndmask_b32_e64 v75, v133, v140, s[0:1]
	v_mul_f32_e32 v123, v44, v44
	v_mul_f32_e32 v130, v32, v32
	v_mul_f32_e32 v90, v23, v23
	v_mul_f32_e32 v137, v16, v16
	ds_bpermute_b32 v43, v186, v43
	v_cndmask_b32_e64 v49, v122, v91, s[0:1]
	v_cndmask_b32_e64 v61, v126, v76, s[0:1]
	v_cndmask_b32_e64 v67, v129, v136, s[0:1]
	ds_bpermute_b32 v79, v186, v75
	v_cndmask_b32_e64 v75, v121, v35, s[0:1]
	v_cndmask_b32_e64 v84, v27, v55, s[0:1]
	v_cndmask_b32_e64 v85, v119, v113, s[0:1]
	v_mul_f32_e32 v131, v31, v31
	v_mul_f32_e32 v138, v15, v15
	ds_bpermute_b32 v49, v186, v49
	v_cndmask_b32_e64 v51, v123, v90, s[0:1]
	ds_bpermute_b32 v61, v186, v61
	ds_bpermute_b32 v67, v186, v67
	v_cndmask_b32_e64 v69, v130, v137, s[0:1]
	ds_bpermute_b32 v83, v186, v75
	s_waitcnt lgkmcnt(9)
	v_pk_add_f32 v[6:7], v[84:85], v[6:7]
	v_cndmask_b32_e64 v84, v19, v38, s[0:1]
	v_cndmask_b32_e64 v85, v74, v127, s[0:1]
	ds_bpermute_b32 v51, v186, v51
	ds_bpermute_b32 v69, v186, v69
	v_cndmask_b32_e64 v71, v131, v138, s[0:1]
	s_waitcnt lgkmcnt(10)
	v_pk_add_f32 v[62:63], v[84:85], v[62:63]
	v_cndmask_b32_e64 v84, v30, v54, s[0:1]
	v_cndmask_b32_e64 v85, v134, v118, s[0:1]
	v_and_b32_e32 v39, 16, v2
	ds_bpermute_b32 v71, v186, v71
	s_waitcnt lgkmcnt(10)
	v_pk_add_f32 v[8:9], v[84:85], v[8:9]
	v_cndmask_b32_e64 v84, v22, v41, s[0:1]
	v_cndmask_b32_e64 v85, v135, v128, s[0:1]
	v_mul_f32_e32 v125, v36, v36
	v_mul_f32_e32 v77, v21, v21
	v_cmp_eq_u32_e32 vcc, 0, v39
	s_waitcnt lgkmcnt(9)
	v_pk_add_f32 v[64:65], v[84:85], v[64:65]
	v_cndmask_b32_e64 v84, v25, v53, s[0:1]
	v_cndmask_b32_e64 v85, v111, v120, s[0:1]
	v_cndmask_b32_e64 v59, v125, v77, s[0:1]
	v_cndmask_b32_e32 v39, v6, v62, vcc
	s_waitcnt lgkmcnt(8)
	v_pk_add_f32 v[42:43], v[84:85], v[42:43]
	v_cndmask_b32_e64 v84, v17, v34, s[0:1]
	v_cndmask_b32_e64 v85, v136, v129, s[0:1]
	v_cndmask_b32_e64 v86, v24, v52, s[0:1]
	v_cndmask_b32_e64 v87, v91, v122, s[0:1]
	v_cndmask_b32_e64 v93, v77, v125, s[0:1]
	v_cndmask_b32_e64 v94, v20, v37, s[0:1]
	v_cndmask_b32_e64 v95, v76, v126, s[0:1]
	v_cndmask_b32_e64 v76, v13, v28, s[0:1]
	v_cndmask_b32_e64 v77, v35, v121, s[0:1]
	ds_bpermute_b32 v74, v187, v39
	v_cndmask_b32_e32 v39, v8, v64, vcc
	s_waitcnt lgkmcnt(5)
	v_pk_add_f32 v[66:67], v[84:85], v[66:67]
	v_pk_add_f32 v[48:49], v[86:87], v[48:49]
	v_cndmask_b32_e64 v86, v16, v32, s[0:1]
	v_cndmask_b32_e64 v87, v137, v130, s[0:1]
	v_cndmask_b32_e64 v88, v23, v44, s[0:1]
	v_cndmask_b32_e64 v89, v90, v123, s[0:1]
	v_pk_add_f32 v[60:61], v[94:95], v[60:61]
	s_waitcnt lgkmcnt(4)
	v_pk_add_f32 v[76:77], v[76:77], v[82:83]
	ds_bpermute_b32 v80, v187, v39
	v_cndmask_b32_e32 v39, v42, v66, vcc
	s_waitcnt lgkmcnt(3)
; __device__ __forceinline__ float wave_reduce32(const float (&v)[32], int lane) {
;     float a[16], b[8], c[4], d[2], e;
;     { const bool h = lane & 32;
; #pragma unroll
;       for (int t = 0; t < 16; ++t) { const float keep = h ? v[t + 16] : v[t], send = h ? v[t] : v[t + 16]; a[t] = keep + __shfl_xor(send, 32); } }
;     { const bool h = lane & 16;
; #pragma unroll
;       for (int t = 0; t < 8; ++t) { const float keep = h ? a[t + 8] : a[t], send = h ? a[t] : a[t + 8]; b[t] = keep + __shfl_xor(send, 16); } }
;     { const bool h = lane & 8;
; #pragma unroll
;       for (int t = 0; t < 4; ++t) { const float keep = h ? b[t + 4] : b[t], send = h ? b[t] : b[t + 4]; c[t] = keep + __shfl_xor(send, 8); } }
;     { const bool h = lane & 4;
; #pragma unroll
;       for (int t = 0; t < 2; ++t) { const float keep = h ? c[t + 2] : c[t], send = h ? c[t] : c[t + 2]; d[t] = keep + __shfl_xor(send, 4); } }
;     { const bool h = lane & 2; const float keep = h ? d[1] : d[0], send = h ? d[0] : d[1]; e = keep + __shfl_xor(send, 2); }
;     e += __shfl_xor(e, 1);
;     return e;
; }
; __device__ __forceinline__ void conv_tile(const Params& p, int l, int item, const bf16* PROJ, bf16* CV, LAS float* sl) {
;     ...
;     const int tl = 16 * ((lane >> 5) & 1) + 8 * ((lane >> 4) & 1) + 4 * ((lane >> 3) & 1) + 2 * ((lane >> 2) & 1) + ((lane >> 1) & 1);
;     __syncthreads();
;     if ((lane & 1) == 0) { part[(tl * 8 + wave) * 2] = r1; part[(tl * 8 + wave) * 2 + 1] = r2; }
	v_pk_add_f32 v[68:69], v[86:87], v[68:69]
	v_pk_add_f32 v[50:51], v[88:89], v[50:51]
	v_cndmask_b32_e64 v88, v15, v31, s[0:1]
	v_cndmask_b32_e64 v89, v138, v131, s[0:1]
	v_cndmask_b32_e32 v35, v60, v76, vcc
	v_mul_f32_e32 v124, v47, v47
	v_mul_f32_e32 v81, v26, v26
	ds_bpermute_b32 v84, v187, v39
	v_cndmask_b32_e32 v39, v48, v68, vcc
	s_waitcnt lgkmcnt(3)
	v_pk_add_f32 v[70:71], v[88:89], v[70:71]
	ds_bpermute_b32 v82, v187, v35
	v_cndmask_b32_e32 v35, v7, v63, vcc
	v_cndmask_b32_e64 v57, v124, v81, s[0:1]
	ds_bpermute_b32 v86, v187, v39
	v_cndmask_b32_e32 v39, v50, v70, vcc
	ds_bpermute_b32 v75, v187, v35
	v_cndmask_b32_e32 v35, v51, v71, vcc
	v_mul_f32_e32 v132, v33, v33
	v_mul_f32_e32 v139, v18, v18
	ds_bpermute_b32 v57, v186, v57
	ds_bpermute_b32 v59, v186, v59
	ds_bpermute_b32 v88, v187, v39
	ds_bpermute_b32 v89, v187, v35
	v_cndmask_b32_e64 v73, v132, v139, s[0:1]
	ds_bpermute_b32 v73, v186, v73
	v_and_b32_e32 v40, 8, v2
	v_cndmask_b32_e64 v90, v26, v47, s[0:1]
	v_cndmask_b32_e64 v91, v81, v124, s[0:1]
	v_cndmask_b32_e64 v92, v21, v36, s[0:1]
	v_cndmask_b32_e32 v7, v63, v7, vcc
	v_cndmask_b32_e32 v6, v62, v6, vcc
	v_cndmask_b32_e32 v51, v71, v51, vcc
	v_cndmask_b32_e32 v50, v70, v50, vcc
	s_waitcnt lgkmcnt(4)
	v_pk_add_f32 v[56:57], v[90:91], v[56:57]
	v_cndmask_b32_e64 v90, v18, v33, s[0:1]
	v_cndmask_b32_e64 v91, v139, v132, s[0:1]
	s_waitcnt lgkmcnt(3)
	v_pk_add_f32 v[58:59], v[92:93], v[58:59]
	v_cndmask_b32_e64 v92, v14, v29, s[0:1]
	v_cndmask_b32_e64 v93, v140, v133, s[0:1]
	v_pk_add_f32 v[6:7], v[6:7], v[74:75]
	s_waitcnt lgkmcnt(1)
	v_pk_add_f32 v[50:51], v[50:51], v[88:89]
	v_cmp_eq_u32_e64 s[0:1], 0, v40
	s_waitcnt lgkmcnt(0)
	v_pk_add_f32 v[72:73], v[90:91], v[72:73]
	v_cndmask_b32_e32 v8, v64, v8, vcc
	v_cndmask_b32_e64 v35, v6, v50, s[0:1]
	ds_bpermute_b32 v62, v180, v35
	v_cndmask_b32_e32 v35, v9, v65, vcc
	v_cndmask_b32_e32 v39, v56, v72, vcc
	ds_bpermute_b32 v81, v187, v35
	v_cndmask_b32_e32 v35, v57, v73, vcc
	ds_bpermute_b32 v90, v187, v39
	ds_bpermute_b32 v91, v187, v35
	v_cndmask_b32_e32 v9, v65, v9, vcc
	v_cndmask_b32_e32 v57, v73, v57, vcc
	v_cndmask_b32_e32 v56, v72, v56, vcc
	s_waitcnt lgkmcnt(2)
	v_pk_add_f32 v[8:9], v[8:9], v[80:81]
	s_waitcnt lgkmcnt(0)
	v_pk_add_f32 v[56:57], v[56:57], v[90:91]
	v_pk_add_f32 v[78:79], v[92:93], v[78:79]
	v_cndmask_b32_e64 v35, v8, v56, s[0:1]
	ds_bpermute_b32 v64, v180, v35
	v_cndmask_b32_e32 v35, v43, v67, vcc
	v_cndmask_b32_e32 v39, v58, v78, vcc
	ds_bpermute_b32 v85, v187, v35
	v_cndmask_b32_e32 v35, v59, v79, vcc
	ds_bpermute_b32 v92, v187, v39
	ds_bpermute_b32 v93, v187, v35
	v_cndmask_b32_e32 v43, v67, v43, vcc
	v_cndmask_b32_e32 v42, v66, v42, vcc
	v_cndmask_b32_e32 v59, v79, v59, vcc
	v_cndmask_b32_e32 v58, v78, v58, vcc
	s_waitcnt lgkmcnt(2)
	v_pk_add_f32 v[42:43], v[42:43], v[84:85]
	s_waitcnt lgkmcnt(0)
	v_pk_add_f32 v[58:59], v[58:59], v[92:93]
	v_cndmask_b32_e32 v48, v68, v48, vcc
	v_cndmask_b32_e64 v35, v42, v58, s[0:1]
	ds_bpermute_b32 v66, v180, v35
	v_cndmask_b32_e32 v35, v49, v69, vcc
	ds_bpermute_b32 v87, v187, v35
	v_cndmask_b32_e32 v35, v61, v77, vcc
	ds_bpermute_b32 v83, v187, v35
	v_cndmask_b32_e32 v49, v69, v49, vcc
	v_cndmask_b32_e32 v61, v77, v61, vcc
	v_cndmask_b32_e32 v60, v76, v60, vcc
	s_waitcnt lgkmcnt(1)
	v_pk_add_f32 v[48:49], v[48:49], v[86:87]
	s_waitcnt lgkmcnt(0)
	v_pk_add_f32 v[60:61], v[60:61], v[82:83]
	v_and_b32_e32 v45, 4, v2
	v_cndmask_b32_e64 v35, v48, v60, s[0:1]
	ds_bpermute_b32 v68, v180, v35
	v_cndmask_b32_e64 v35, v7, v51, s[0:1]
	ds_bpermute_b32 v63, v180, v35
	v_cndmask_b32_e64 v35, v43, v59, s[0:1]
	ds_bpermute_b32 v67, v180, v35
	v_cndmask_b32_e64 v7, v51, v7, s[0:1]
	v_cndmask_b32_e64 v6, v50, v6, s[0:1]
	v_cndmask_b32_e64 v43, v59, v43, s[0:1]
	v_cndmask_b32_e64 v42, v58, v42, s[0:1]
	s_waitcnt lgkmcnt(1)
	v_pk_add_f32 v[6:7], v[6:7], v[62:63]
	s_waitcnt lgkmcnt(0)
	v_pk_add_f32 v[42:43], v[42:43], v[66:67]
	v_cmp_eq_u32_e32 vcc, 0, v45
	v_cndmask_b32_e64 v8, v56, v8, s[0:1]
	v_cndmask_b32_e64 v48, v60, v48, s[0:1]
	v_cndmask_b32_e32 v35, v6, v42, vcc
	ds_bpermute_b32 v50, v179, v35
	v_cndmask_b32_e64 v35, v9, v57, s[0:1]
	ds_bpermute_b32 v65, v180, v35
	v_cndmask_b32_e64 v35, v49, v61, s[0:1]
	ds_bpermute_b32 v69, v180, v35
	v_cndmask_b32_e64 v9, v57, v9, s[0:1]
	v_cndmask_b32_e64 v49, v61, v49, s[0:1]
	s_waitcnt lgkmcnt(1)
	v_pk_add_f32 v[8:9], v[8:9], v[64:65]
	v_and_b32_e32 v46, 2, v2
	s_waitcnt lgkmcnt(0)
	v_pk_add_f32 v[48:49], v[48:49], v[68:69]
	v_cndmask_b32_e32 v6, v42, v6, vcc
	v_cndmask_b32_e32 v35, v8, v48, vcc
	ds_bpermute_b32 v56, v179, v35
	v_cndmask_b32_e32 v35, v7, v43, vcc
	ds_bpermute_b32 v51, v179, v35
	v_cndmask_b32_e32 v35, v9, v49, vcc
	ds_bpermute_b32 v57, v179, v35
	v_cndmask_b32_e32 v7, v43, v7, vcc
	v_cndmask_b32_e32 v9, v49, v9, vcc
	v_cndmask_b32_e32 v8, v48, v8, vcc
	s_waitcnt lgkmcnt(1)
	v_pk_add_f32 v[6:7], v[6:7], v[50:51]
	s_waitcnt lgkmcnt(0)
	v_pk_add_f32 v[8:9], v[8:9], v[56:57]
	v_cmp_eq_u32_e32 vcc, 0, v46
	v_readfirstlane_b32 s9, v2
	v_readlane_b32 s81, v251, 34
	v_cndmask_b32_e32 v35, v6, v8, vcc
	ds_bpermute_b32 v42, v178, v35
	v_cndmask_b32_e32 v35, v7, v9, vcc
	ds_bpermute_b32 v43, v178, v35
	v_cndmask_b32_e32 v7, v9, v7, vcc
	v_cndmask_b32_e32 v6, v8, v6, vcc
	v_and_b32_e32 v35, 1, v2
	v_cmp_eq_u32_e32 vcc, 0, v35
	s_waitcnt lgkmcnt(0)
	v_pk_add_f32 v[6:7], v[6:7], v[42:43]
	ds_bpermute_b32 v8, v162, v6
	ds_bpermute_b32 v9, v162, v7
	v_readlane_b32 s82, v251, 35
	v_readlane_b32 s83, v251, 36
	v_readlane_b32 s86, v251, 39
	v_readlane_b32 s87, v251, 40
	v_readlane_b32 s88, v251, 41
	v_readlane_b32 s89, v251, 42
	v_readlane_b32 s90, v251, 43
	v_readlane_b32 s91, v251, 44
	v_readlane_b32 s92, v251, 45
	v_readlane_b32 s93, v251, 46
	v_readlane_b32 s94, v251, 47
	v_readlane_b32 s95, v251, 48
	s_waitcnt lgkmcnt(0)
	s_barrier
	s_and_saveexec_b64 s[0:1], vcc
	s_cbranch_execz .LBB0_347
	s_ashr_i32 s9, s9, 5
	s_lshl_b32 s9, s9, 2
	v_lshlrev_b32_e32 v35, 5, v2
	s_and_b32 s9, s9, -8
	v_and_b32_e32 v35, 0x7c0, v35
	s_add_i32 s9, s9, 0
	v_add_u32_e32 v35, s9, v35
	v_add_u32_e32 v35, 0x20000, v35
	v_pk_add_f32 v[6:7], v[6:7], v[8:9]
	ds_write_b64 v35, v[6:7]
